# spectra FFT blocks: half-rate ds_read2_b64 split into full-rate ds_read_b64 pairs (120 sites), lgkmcnt recounted
# speedup vs baseline: 1.0027x; 1.0017x over previous
.LBB0_368:
	s_or_b64 exec, exec, s[10:11]
	v_mov_b32_e32 v8, s51
	s_lshl_b32 s10, s55, 9
	v_add_u32_e32 v56, 0x2200, v170
	s_waitcnt lgkmcnt(0)
	s_barrier
	ds_read_b64_tr_b16 v[0:1], v169
	ds_read_b64_tr_b16 v[2:3], v169 offset:768
	ds_read2_b32 v[12:13], v8 offset1:4
	ds_read2_b32 v[14:15], v8 offset0:8 offset1:12
	ds_read2_b32 v[104:105], v8 offset0:16 offset1:20
	ds_read_b64 v[4:5], v170
	ds_read_b64 v[6:7], v170 offset:8
	ds_read2_b32 v[108:109], v8 offset0:24 offset1:28
	ds_read_b64 v[8:9], v56
	ds_read_b64 v[10:11], v56 offset:8
	s_or_b32 s10, s54, s10
	s_or_b32 s10, s10, s50
	s_ashr_i32 s11, s10, 31
	s_lshl_b64 s[12:13], s[10:11], 2
	s_waitcnt lgkmcnt(3)
	v_mfma_f32_32x32x16_bf16 v[18:33], v[0:3], v[4:7], 0
	s_add_u32 s12, s22, s12
	s_addc_u32 s13, s23, s13
	global_load_dword v106, v97, s[12:13]
	v_add_u32_e32 v60, 0x2220, v170
	v_add_u32_e32 v78, 0x2240, v170
	v_add_u32_e32 v88, 0x2260, v170
	s_waitcnt lgkmcnt(0)
	v_mfma_f32_32x32x16_bf16 v[34:49], v[0:3], v[8:11], 0
	ds_read_b64_tr_b16 v[0:1], v169 offset:3072
	ds_read_b64_tr_b16 v[2:3], v169 offset:3840
	ds_read_b64 v[4:5], v170 offset:32
	ds_read_b64 v[6:7], v170 offset:40
	ds_read_b64 v[8:9], v60
	ds_read_b64 v[10:11], v60 offset:8
	v_add_u32_e32 v178, 0x4000, v171
	v_add_u32_e32 v179, 0x2000, v171
	s_lshl_b64 s[10:11], s[10:11], 14
	s_add_i32 s49, s49, s46
	s_waitcnt lgkmcnt(2)
	v_mfma_f32_32x32x16_bf16 v[18:33], v[0:3], v[4:7], v[18:33]
	s_cmpk_lt_i32 s49, 0x100
	s_waitcnt lgkmcnt(0)
	v_mfma_f32_32x32x16_bf16 v[34:49], v[0:3], v[8:11], v[34:49]
	ds_read_b64_tr_b16 v[0:1], v169 offset:6144
	ds_read_b64_tr_b16 v[2:3], v169 offset:6912
	ds_read_b64 v[4:5], v170 offset:64
	ds_read_b64 v[6:7], v170 offset:72
	ds_read_b64 v[8:9], v78
	ds_read_b64 v[10:11], v78 offset:8
	s_waitcnt lgkmcnt(2)
	v_mfma_f32_32x32x16_bf16 v[18:33], v[0:3], v[4:7], v[18:33]
	v_add_f32_e32 v4, 0, v12
	v_add_f32_e32 v12, v4, v13
	ds_read_b64_tr_b16 v[4:5], v169 offset:9216
	ds_read_b64_tr_b16 v[6:7], v169 offset:9984
	s_waitcnt lgkmcnt(2)
	v_mfma_f32_32x32x16_bf16 v[34:49], v[0:3], v[8:11], v[34:49]
	v_add_f32_e32 v0, v12, v14
	v_add_f32_e32 v8, v0, v15
	ds_read_b64 v[0:1], v170 offset:96
	ds_read_b64 v[2:3], v170 offset:104
	v_add_f32_e32 v104, v8, v104
	ds_read_b64 v[8:9], v88
	ds_read_b64 v[10:11], v88 offset:8
	s_waitcnt lgkmcnt(0)
	v_mfma_f32_32x32x16_bf16 v[34:49], v[4:7], v[8:11], v[34:49]
	v_mfma_f32_32x32x16_bf16 v[18:33], v[4:7], v[0:3], v[18:33]
	ds_read_b32 v2, v130
	ds_read_b32 v3, v131
	ds_read_b32 v12, v132
	ds_read_b32 v13, v133
	ds_read_b32 v14, v134
	ds_read_b32 v15, v135
	ds_read_b32 v16, v136
	ds_read_b32 v17, v137
	s_waitcnt lgkmcnt(6)
	v_cvt_f32_f16_e32 v1, v3
	v_cvt_f32_f16_e32 v0, v2
	v_cvt_f32_f16_sdwa v3, v3 dst_sel:DWORD dst_unused:UNUSED_PAD src0_sel:WORD_1
	v_cvt_f32_f16_sdwa v2, v2 dst_sel:DWORD dst_unused:UNUSED_PAD src0_sel:WORD_1
	s_waitcnt lgkmcnt(4)
	v_cvt_f32_f16_sdwa v7, v13 dst_sel:DWORD dst_unused:UNUSED_PAD src0_sel:WORD_1
	v_cvt_f32_f16_sdwa v6, v12 dst_sel:DWORD dst_unused:UNUSED_PAD src0_sel:WORD_1
	v_pk_mul_f32 v[4:5], v[34:35], v[2:3]
	s_nop 0
	v_pk_fma_f32 v[52:53], v[18:19], v[0:1], v[4:5] neg_lo:[0,0,1] neg_hi:[0,0,1]
	v_cvt_f32_f16_e32 v5, v13
	v_cvt_f32_f16_e32 v4, v12
	v_pk_mul_f32 v[2:3], v[18:19], v[2:3]
	s_nop 0
	v_pk_fma_f32 v[34:35], v[34:35], v[0:1], v[2:3]
	v_pk_mul_f32 v[0:1], v[36:37], v[6:7]
	s_waitcnt lgkmcnt(2)
	v_cvt_f32_f16_sdwa v3, v15 dst_sel:DWORD dst_unused:UNUSED_PAD src0_sel:WORD_1
	v_cvt_f32_f16_sdwa v2, v14 dst_sel:DWORD dst_unused:UNUSED_PAD src0_sel:WORD_1
	v_pk_fma_f32 v[50:51], v[20:21], v[4:5], v[0:1] neg_lo:[0,0,1] neg_hi:[0,0,1]
	v_cvt_f32_f16_e32 v1, v15
	v_cvt_f32_f16_e32 v0, v14
	v_pk_mul_f32 v[6:7], v[20:21], v[6:7]
	v_cvt_pk_bf16_f32 v76, v34, v35
	v_pk_fma_f32 v[36:37], v[36:37], v[4:5], v[6:7]
	v_pk_mul_f32 v[4:5], v[38:39], v[2:3]
	s_waitcnt lgkmcnt(0)
	v_cvt_f32_f16_sdwa v7, v17 dst_sel:DWORD dst_unused:UNUSED_PAD src0_sel:WORD_1
	v_cvt_f32_f16_sdwa v6, v16 dst_sel:DWORD dst_unused:UNUSED_PAD src0_sel:WORD_1
	v_pk_fma_f32 v[54:55], v[22:23], v[0:1], v[4:5] neg_lo:[0,0,1] neg_hi:[0,0,1]
	v_cvt_f32_f16_e32 v5, v17
	v_cvt_f32_f16_e32 v4, v16
	v_pk_mul_f32 v[2:3], v[22:23], v[2:3]
	v_cvt_pk_bf16_f32 v77, v36, v37
	v_pk_fma_f32 v[38:39], v[38:39], v[0:1], v[2:3]
	v_pk_mul_f32 v[0:1], v[40:41], v[6:7]
	v_pk_mul_f32 v[6:7], v[24:25], v[6:7]
	v_pk_fma_f32 v[64:65], v[24:25], v[4:5], v[0:1] neg_lo:[0,0,1] neg_hi:[0,0,1]
	ds_read_b32 v0, v138
	ds_read_b32 v2, v139
	ds_read_b32 v8, v140
	ds_read_b32 v9, v141
	ds_read_b32 v10, v142
	ds_read_b32 v11, v143
	ds_read_b32 v61, v144
	ds_read_b32 v62, v145
	s_waitcnt lgkmcnt(6)
	v_cvt_f32_f16_e32 v1, v2
	v_cvt_f32_f16_sdwa v3, v2 dst_sel:DWORD dst_unused:UNUSED_PAD src0_sel:WORD_1
	v_cvt_f32_f16_sdwa v2, v0 dst_sel:DWORD dst_unused:UNUSED_PAD src0_sel:WORD_1
	v_cvt_f32_f16_e32 v0, v0
	v_pk_fma_f32 v[66:67], v[40:41], v[4:5], v[6:7]
	s_waitcnt lgkmcnt(4)
	v_cvt_f32_f16_sdwa v7, v9 dst_sel:DWORD dst_unused:UNUSED_PAD src0_sel:WORD_1
	v_pk_mul_f32 v[4:5], v[42:43], v[2:3]
	v_cvt_f32_f16_sdwa v6, v8 dst_sel:DWORD dst_unused:UNUSED_PAD src0_sel:WORD_1
	v_pk_fma_f32 v[72:73], v[26:27], v[0:1], v[4:5] neg_lo:[0,0,1] neg_hi:[0,0,1]
	v_cvt_f32_f16_e32 v5, v9
	v_cvt_f32_f16_e32 v4, v8
	v_pk_mul_f32 v[2:3], v[26:27], v[2:3]
	ds_read_b64_tr_b16 v[16:17], v169 offset:64
	ds_read_b64_tr_b16 v[18:19], v169 offset:832
	v_pk_fma_f32 v[74:75], v[42:43], v[0:1], v[2:3]
	v_pk_mul_f32 v[0:1], v[44:45], v[6:7]
	s_waitcnt lgkmcnt(4)
	v_cvt_f32_f16_sdwa v27, v11 dst_sel:DWORD dst_unused:UNUSED_PAD src0_sel:WORD_1
	v_pk_fma_f32 v[80:81], v[28:29], v[4:5], v[0:1] neg_lo:[0,0,1] neg_hi:[0,0,1]
	v_pk_mul_f32 v[0:1], v[28:29], v[6:7]
	v_cvt_f32_f16_sdwa v26, v10 dst_sel:DWORD dst_unused:UNUSED_PAD src0_sel:WORD_1
	v_pk_fma_f32 v[82:83], v[44:45], v[4:5], v[0:1]
	ds_read_b64 v[0:1], v170
	ds_read_b64 v[2:3], v170 offset:8
	ds_read_b64 v[20:21], v56
	ds_read_b64 v[22:23], v56 offset:8
	v_cvt_f32_f16_e32 v25, v11
	v_cvt_f32_f16_e32 v24, v10
	v_pk_mul_f32 v[28:29], v[46:47], v[26:27]
	v_pk_mul_f32 v[26:27], v[30:31], v[26:27]
	s_waitcnt lgkmcnt(2)
	v_mfma_f32_32x32x16_bf16 v[0:15], v[16:19], v[0:3], 0
	v_fma_f32 v84, v30, v24, -v28
	v_fma_f32 v85, v31, v25, -v29
	v_fma_f32 v86, v46, v24, v26
	v_fma_f32 v87, v47, v25, v27
	ds_read_b64_tr_b16 v[42:43], v169 offset:3136
	ds_read_b64_tr_b16 v[44:45], v169 offset:3904
	v_cvt_f32_f16_sdwa v41, v62 dst_sel:DWORD dst_unused:UNUSED_PAD src0_sel:WORD_1
	v_cvt_f32_f16_sdwa v40, v61 dst_sel:DWORD dst_unused:UNUSED_PAD src0_sel:WORD_1
	ds_read_b64 v[56:57], v170 offset:32
	ds_read_b64 v[58:59], v170 offset:40
	s_waitcnt lgkmcnt(4)
	v_mfma_f32_32x32x16_bf16 v[16:31], v[16:19], v[20:23], 0
	v_cvt_f32_f16_e32 v47, v62
	v_cvt_f32_f16_e32 v46, v61
	ds_read_b64 v[62:63], v60 offset:8
	ds_read_b64 v[60:61], v60
	v_mul_f32_e64 v68, v48, v40
	v_mul_f32_e64 v69, v49, v41
	v_cvt_pk_bf16_f32 v70, v54, v55
	v_cvt_pk_bf16_f32 v71, v64, v65
	s_waitcnt lgkmcnt(0)
	v_mfma_f32_32x32x16_bf16 v[16:31], v[42:45], v[60:63], v[16:31]
	v_cvt_pk_bf16_f32 v64, v72, v73
	v_cvt_pk_bf16_f32 v65, v80, v81
	v_cvt_pk_bf16_f32 v73, v82, v83
	v_cvt_pk_bf16_f32 v79, v66, v67
	v_cvt_pk_bf16_f32 v66, v84, v85
	v_cvt_pk_bf16_f32 v72, v74, v75
	v_cvt_pk_bf16_f32 v74, v86, v87
	v_mfma_f32_32x32x16_bf16 v[0:15], v[42:45], v[56:59], v[0:15]
	v_fma_f32 v56, v32, v46, -v68
	v_fma_f32 v57, v33, v47, -v69
	v_mul_f32_e64 v32, v32, v40
	v_mul_f32_e64 v33, v33, v41
	v_cvt_pk_bf16_f32 v68, v52, v53
	v_pk_fma_f32 v[40:41], v[48:49], v[46:47], v[32:33]
	ds_read_b64_tr_b16 v[46:47], v169 offset:6208
	ds_read_b64_tr_b16 v[48:49], v169 offset:6976
	v_cvt_pk_bf16_f32 v69, v50, v51
	ds_read_b64 v[42:43], v170 offset:64
	ds_read_b64 v[44:45], v170 offset:72
	ds_read_b64 v[50:51], v78
	ds_read_b64 v[52:53], v78 offset:8
	s_waitcnt lgkmcnt(0)
	v_mfma_f32_32x32x16_bf16 v[16:31], v[46:49], v[50:53], v[16:31]
	v_cvt_pk_bf16_f32 v78, v38, v39
	ds_read_b64_tr_b16 v[32:33], v169 offset:9280
	ds_read_b64_tr_b16 v[34:35], v169 offset:10048
	ds_read_b64 v[36:37], v88
	ds_read_b64 v[38:39], v88 offset:8
	v_cvt_pk_bf16_f32 v67, v56, v57
	v_cvt_pk_bf16_f32 v75, v40, v41
	v_mfma_f32_32x32x16_bf16 v[0:15], v[46:49], v[42:45], v[0:15]
	ds_read_b64 v[42:43], v170 offset:96
	ds_read_b64 v[44:45], v170 offset:104
	s_waitcnt lgkmcnt(2)
	v_mfma_f32_32x32x16_bf16 v[16:31], v[32:35], v[36:39], v[16:31]
	s_waitcnt lgkmcnt(0)
	v_mfma_f32_32x32x16_bf16 v[0:15], v[32:35], v[42:45], v[0:15]
	ds_read_b32 v42, v146
	ds_read_b32 v43, v147
	ds_read_b32 v54, v148
	ds_read_b32 v55, v149
	ds_read_b32 v60, v150
	ds_read_b32 v61, v151
	ds_read_b32 v107, v152
	ds_read_b32 v176, v153
	ds_read_b64 v[80:81], v171
	ds_read_b64 v[82:83], v171 offset:16
	s_waitcnt lgkmcnt(8)
	v_cvt_f32_f16_e32 v49, v43
	v_cvt_f32_f16_e32 v48, v42
	v_cvt_f32_f16_sdwa v43, v43 dst_sel:DWORD dst_unused:UNUSED_PAD src0_sel:WORD_1
	v_cvt_f32_f16_sdwa v42, v42 dst_sel:DWORD dst_unused:UNUSED_PAD src0_sel:WORD_1
	s_waitcnt lgkmcnt(6)
	v_cvt_f32_f16_sdwa v59, v55 dst_sel:DWORD dst_unused:UNUSED_PAD src0_sel:WORD_1
	ds_read_b64 v[50:51], v178 offset:1024
	ds_read_b64 v[52:53], v178 offset:1040
	v_cvt_f32_f16_sdwa v58, v54 dst_sel:DWORD dst_unused:UNUSED_PAD src0_sel:WORD_1
	v_pk_mul_f32 v[32:33], v[16:17], v[42:43]
	s_waitcnt lgkmcnt(6)
	v_cvt_f32_f16_e32 v93, v61
	v_pk_fma_f32 v[84:85], v[0:1], v[48:49], v[32:33] neg_lo:[0,0,1] neg_hi:[0,0,1]
	v_pk_mul_f32 v[0:1], v[0:1], v[42:43]
	s_waitcnt lgkmcnt(2)
	v_mfma_f32_32x32x16_bf16 v[32:47], v[80:83], v[68:71], 0
	v_fma_f32 v86, v16, v48, v0
	v_fma_f32 v87, v17, v49, v1
	v_cvt_f32_f16_e32 v1, v55
	v_cvt_f32_f16_e32 v0, v54
	ds_read_b64 v[54:55], v179 offset:512
	ds_read_b64 v[56:57], v179 offset:528
	v_pk_mul_f32 v[16:17], v[18:19], v[58:59]
	ds_read_b32 v180, v154
	ds_read_b32 v181, v155
	ds_read_b32 v182, v156
	ds_read_b32 v183, v157
	ds_read_b32 v184, v158
	ds_read_b32 v185, v159
	ds_read_b32 v186, v160
	ds_read_b32 v187, v162
	v_pk_fma_f32 v[88:89], v[2:3], v[0:1], v[16:17] neg_lo:[0,0,1] neg_hi:[0,0,1]
	v_pk_mul_f32 v[2:3], v[2:3], v[58:59]
	s_waitcnt lgkmcnt(10)
	v_mfma_f32_32x32x16_bf16 v[32:47], v[50:53], v[76:79], v[32:47]
	v_fma_f32 v90, v18, v0, v2
	v_fma_f32 v91, v19, v1, v3
	ds_read_b64 v[0:1], v171 offset:32
	ds_read_b64 v[2:3], v171 offset:48
	v_cvt_f32_f16_e32 v92, v60
	v_cvt_f32_f16_sdwa v95, v61 dst_sel:DWORD dst_unused:UNUSED_PAD src0_sel:WORD_1
	v_cvt_f32_f16_sdwa v94, v60 dst_sel:DWORD dst_unused:UNUSED_PAD src0_sel:WORD_1
	v_cvt_f32_f16_e32 v175, v176
	v_cvt_f32_f16_sdwa v177, v176 dst_sel:DWORD dst_unused:UNUSED_PAD src0_sel:WORD_1
	s_waitcnt lgkmcnt(10)
	v_mfma_f32_32x32x16_bf16 v[48:63], v[54:57], v[68:71], 0
	v_mul_f32_e64 v16, v20, v94
	v_mul_f32_e64 v17, v21, v95
	v_cvt_f32_f16_sdwa v176, v107 dst_sel:DWORD dst_unused:UNUSED_PAD src0_sel:WORD_1
	v_fma_f32 v172, v4, v92, -v16
	v_fma_f32 v173, v5, v93, -v17
	ds_read_b64 v[16:17], v178 offset:1056
	ds_read_b64 v[18:19], v178 offset:1072
	v_cvt_f32_f16_e32 v174, v107
	v_pk_mul_f32 v[4:5], v[4:5], v[94:95]
	s_waitcnt lgkmcnt(10)
	v_cvt_f32_f16_sdwa v95, v181 dst_sel:DWORD dst_unused:UNUSED_PAD src0_sel:WORD_1
	v_mfma_f32_32x32x16_bf16 v[48:63], v[80:83], v[76:79], v[48:63]
	ds_read_b64 v[80:81], v179 offset:544
	ds_read_b64 v[82:83], v179 offset:560
	v_fma_f32 v20, v20, v92, v4
	v_fma_f32 v21, v21, v93, v5
	v_mul_f32_e64 v4, v22, v176
	v_mul_f32_e64 v5, v23, v177
	v_cvt_f32_f16_sdwa v94, v180 dst_sel:DWORD dst_unused:UNUSED_PAD src0_sel:WORD_1
	v_pk_fma_f32 v[92:93], v[6:7], v[174:175], v[4:5] neg_lo:[0,0,1] neg_hi:[0,0,1]
	v_cvt_f32_f16_e32 v5, v181
	v_cvt_f32_f16_e32 v4, v180
	s_waitcnt lgkmcnt(4)
	v_mfma_f32_32x32x16_bf16 v[32:47], v[0:3], v[64:67], v[32:47]
	v_mul_f32_e64 v6, v6, v176
	v_mul_f32_e64 v7, v7, v177
	s_waitcnt lgkmcnt(2)
	v_mfma_f32_32x32x16_bf16 v[32:47], v[16:19], v[72:75], v[32:47]
	v_fma_f32 v16, v22, v174, v6
	v_fma_f32 v17, v23, v175, v7
	v_mul_f32_e64 v6, v24, v94
	v_mul_f32_e64 v7, v25, v95
	v_fma_f32 v22, v8, v4, -v6
	v_fma_f32 v23, v9, v5, -v7
	v_pk_mul_f32 v[6:7], v[8:9], v[94:95]
	v_cvt_f32_f16_sdwa v95, v183 dst_sel:DWORD dst_unused:UNUSED_PAD src0_sel:WORD_1
	v_pk_fma_f32 v[8:9], v[24:25], v[4:5], v[6:7]
	s_waitcnt lgkmcnt(0)
	v_mfma_f32_32x32x16_bf16 v[48:63], v[80:83], v[64:67], v[48:63]
	ds_read_b64 v[4:5], v171 offset:64
	ds_read_b64 v[6:7], v171 offset:80
	v_cvt_f32_f16_sdwa v94, v182 dst_sel:DWORD dst_unused:UNUSED_PAD src0_sel:WORD_1
	v_cvt_f32_f16_e32 v25, v183
	v_cvt_f32_f16_e32 v24, v182
	v_cvt_pk_bf16_f32 v80, v84, v85
	v_cvt_pk_bf16_f32 v81, v88, v89
	v_cvt_pk_bf16_f32 v82, v172, v173
	v_mfma_f32_32x32x16_bf16 v[48:63], v[0:3], v[72:75], v[48:63]
	v_mul_f32_e64 v0, v26, v94
	v_mul_f32_e64 v1, v27, v95
	v_cvt_pk_bf16_f32 v83, v92, v93
	v_fma_f32 v174, v10, v24, -v0
	v_fma_f32 v175, v11, v25, -v1
	ds_read_b64 v[0:1], v178 offset:1088
	ds_read_b64 v[2:3], v178 offset:1104
	v_cvt_pk_bf16_f32 v84, v86, v87
	v_cvt_pk_bf16_f32 v87, v16, v17
	ds_read_b64 v[16:17], v179 offset:576
	ds_read_b64 v[18:19], v179 offset:592
	s_waitcnt lgkmcnt(4)
	v_mfma_f32_32x32x16_bf16 v[32:47], v[4:7], v[80:83], v[32:47]
	v_cvt_f32_f16_sdwa v93, v185 dst_sel:DWORD dst_unused:UNUSED_PAD src0_sel:WORD_1
	v_cvt_f32_f16_sdwa v92, v184 dst_sel:DWORD dst_unused:UNUSED_PAD src0_sel:WORD_1
	v_cvt_f32_f16_e32 v89, v185
	v_cvt_f32_f16_e32 v88, v184
	v_cvt_pk_bf16_f32 v85, v90, v91
	v_cvt_pk_bf16_f32 v86, v20, v21
	s_waitcnt lgkmcnt(0)
	v_mfma_f32_32x32x16_bf16 v[48:63], v[16:19], v[80:83], v[48:63]
	v_cvt_f32_f16_sdwa v19, v187 dst_sel:DWORD dst_unused:UNUSED_PAD src0_sel:WORD_1
	v_cvt_f32_f16_sdwa v18, v186 dst_sel:DWORD dst_unused:UNUSED_PAD src0_sel:WORD_1
	v_cvt_f32_f16_e32 v17, v187
	v_cvt_f32_f16_e32 v16, v186
	v_mfma_f32_32x32x16_bf16 v[32:47], v[0:3], v[84:87], v[32:47]
	v_mul_f32_e64 v0, v10, v94
	v_mul_f32_e64 v1, v11, v95
	v_fma_f32 v10, v26, v24, v0
	v_fma_f32 v11, v27, v25, v1
	v_mul_f32_e64 v0, v28, v92
	v_mul_f32_e64 v1, v29, v93
	v_pk_fma_f32 v[20:21], v[12:13], v[88:89], v[0:1] neg_lo:[0,0,1] neg_hi:[0,0,1]
	v_pk_mul_f32 v[0:1], v[12:13], v[92:93]
	v_cvt_pk_bf16_f32 v92, v8, v9
	v_pk_fma_f32 v[12:13], v[28:29], v[88:89], v[0:1]
	ds_read_b64 v[0:1], v171 offset:96
	ds_read_b64 v[2:3], v171 offset:112
	v_cvt_pk_bf16_f32 v93, v10, v11
	ds_read_b64 v[8:9], v179 offset:608
	ds_read_b64 v[10:11], v179 offset:624
	v_mfma_f32_32x32x16_bf16 v[48:63], v[4:7], v[84:87], v[48:63]
	v_mul_f32_e64 v4, v30, v18
	v_mul_f32_e64 v5, v31, v19
	v_cvt_pk_bf16_f32 v88, v22, v23
	v_fma_f32 v4, v14, v16, -v4
	v_fma_f32 v5, v15, v17, -v5
	v_cvt_pk_bf16_f32 v89, v174, v175
	v_cvt_pk_bf16_f32 v90, v20, v21
	v_cvt_pk_bf16_f32 v91, v4, v5
	ds_read_b64 v[4:5], v178 offset:1120
	ds_read_b64 v[6:7], v178 offset:1136
	v_pk_mul_f32 v[14:15], v[14:15], v[18:19]
	s_waitcnt lgkmcnt(4)
	v_mfma_f32_32x32x16_bf16 v[32:47], v[0:3], v[88:91], v[32:47]
	v_fma_f32 v14, v30, v16, v14
	v_fma_f32 v15, v31, v17, v15
	v_cvt_pk_bf16_f32 v94, v12, v13
	v_cvt_pk_bf16_f32 v95, v14, v15
	s_waitcnt lgkmcnt(2)
	v_mfma_f32_32x32x16_bf16 v[48:63], v[8:11], v[88:91], v[48:63]
	s_waitcnt lgkmcnt(0)
	v_mfma_f32_32x32x16_bf16 v[32:47], v[4:7], v[92:95], v[32:47]
	v_add_f32_e32 v4, v104, v105
	v_add_f32_e32 v4, v4, v108
	v_add_f32_e32 v4, v4, v109
	v_add_f32_e32 v4, 0x358637bd, v4
	v_mul_f32_e32 v5, 0x4b800000, v4
	v_cmp_gt_f32_e32 vcc, s44, v4
	v_mfma_f32_32x32x16_bf16 v[48:63], v[0:3], v[92:95], v[48:63]
	s_nop 0
	v_cndmask_b32_e32 v4, v4, v5, vcc
	v_rsq_f32_e32 v4, v4
	s_nop 0
	v_mul_f32_e32 v5, 0x45800000, v4
	v_cndmask_b32_e32 v107, v4, v5, vcc
	s_waitcnt vmcnt(0)
	v_pk_mul_f32 v[104:105], v[106:107], s[26:27] op_sel_hi:[1,0]
	v_lshl_add_u64 v[106:107], v[102:103], 0, s[10:11]
	v_fma_f32 v0, v105, v32, v104
	s_nop 1
	v_mul_f32_e32 v1, v105, v48
	v_cvt_pk_bf16_f32 v0, v0, v1
	global_store_dword v[106:107], v0, off
	v_fma_f32 v0, v105, v33, v104
	v_mul_f32_e32 v1, v105, v49
	v_cvt_pk_bf16_f32 v0, v0, v1
	global_store_dword v[106:107], v0, off offset:256
	v_fma_f32 v0, v105, v34, v104
	v_mul_f32_e32 v1, v105, v50
	v_cvt_pk_bf16_f32 v0, v0, v1
	global_store_dword v[106:107], v0, off offset:512
	v_fma_f32 v0, v105, v35, v104
	v_mul_f32_e32 v1, v105, v51
	v_cvt_pk_bf16_f32 v0, v0, v1
	global_store_dword v[106:107], v0, off offset:768
	v_fma_f32 v0, v105, v36, v104
	v_mul_f32_e32 v1, v105, v52
	v_cvt_pk_bf16_f32 v0, v0, v1
	global_store_dword v[106:107], v0, off offset:2048
	v_fma_f32 v0, v105, v37, v104
	v_mul_f32_e32 v1, v105, v53
	v_cvt_pk_bf16_f32 v0, v0, v1
	global_store_dword v[106:107], v0, off offset:2304
	v_fma_f32 v0, v105, v38, v104
	v_mul_f32_e32 v1, v105, v54
	v_add_u32_e32 v48, 0x1000, v171
	v_cvt_pk_bf16_f32 v0, v0, v1
	ds_read_b64 v[34:35], v48 offset:256
	ds_read_b64 v[36:37], v48 offset:272
	global_store_dword v[106:107], v0, off offset:2560
	v_fma_f32 v0, v105, v39, v104
	v_mul_f32_e32 v1, v105, v55
	v_add_co_u32_e32 v38, vcc, s1, v106
	v_cvt_pk_bf16_f32 v0, v0, v1
	s_nop 0
	v_addc_co_u32_e32 v39, vcc, 0, v107, vcc
	global_store_dword v[106:107], v0, off offset:2816
	v_fma_f32 v0, v105, v40, v104
	v_mul_f32_e32 v1, v105, v56
	v_add_co_u32_e32 v32, vcc, s45, v106
	v_cvt_pk_bf16_f32 v0, v0, v1
	s_nop 0
	v_addc_co_u32_e32 v33, vcc, 0, v107, vcc
	global_store_dword v[32:33], v0, off offset:-4096
	v_fma_f32 v0, v105, v41, v104
	v_mul_f32_e32 v1, v105, v57
	v_cvt_pk_bf16_f32 v0, v0, v1
	global_store_dword v[38:39], v0, off offset:256
	v_fma_f32 v0, v105, v42, v104
	v_mul_f32_e32 v1, v105, v58
	v_add_u32_e32 v42, 0x5000, v171
	v_cvt_pk_bf16_f32 v0, v0, v1
	ds_read_b64 v[16:17], v42 offset:1280
	ds_read_b64 v[18:19], v42 offset:1296
	global_store_dword v[38:39], v0, off offset:512
	v_fma_f32 v20, v105, v43, v104
	s_waitcnt lgkmcnt(2)
	v_mfma_f32_32x32x16_bf16 v[0:15], v[34:37], v[68:71], 0
	v_mul_f32_e32 v21, v105, v59
	v_cvt_pk_bf16_f32 v20, v20, v21
	v_add_u32_e32 v43, 0x3000, v171
	global_store_dword v[38:39], v20, off offset:768
	ds_read_b64 v[20:21], v43 offset:768
	ds_read_b64 v[22:23], v43 offset:784
	v_fma_f32 v24, v105, v44, v104
	v_mul_f32_e32 v25, v105, v60
	s_waitcnt lgkmcnt(2)
	v_mfma_f32_32x32x16_bf16 v[0:15], v[16:19], v[76:79], v[0:15]
	v_cvt_pk_bf16_f32 v16, v24, v25
	global_store_dword v[38:39], v16, off offset:2048
	v_fma_f32 v16, v105, v45, v104
	v_mul_f32_e32 v17, v105, v61
	v_cvt_pk_bf16_f32 v16, v16, v17
	global_store_dword v[38:39], v16, off offset:2304
	v_fma_f32 v40, v105, v46, v104
	s_waitcnt lgkmcnt(0)
	v_mfma_f32_32x32x16_bf16 v[16:31], v[20:23], v[68:71], 0
	v_mul_f32_e32 v41, v105, v62
	v_cvt_pk_bf16_f32 v40, v40, v41
	global_store_dword v[38:39], v40, off offset:2560
	v_fma_f32 v40, v105, v47, v104
	v_mul_f32_e32 v41, v105, v63
	v_cvt_pk_bf16_f32 v40, v40, v41
	global_store_dword v[38:39], v40, off offset:2816
	v_mfma_f32_32x32x16_bf16 v[16:31], v[34:37], v[76:79], v[16:31]
	ds_read_b64 v[34:35], v48 offset:288
	ds_read_b64 v[36:37], v48 offset:304
	ds_read_b64 v[38:39], v42 offset:1312
	ds_read_b64 v[40:41], v42 offset:1328
	s_waitcnt lgkmcnt(2)
	v_mfma_f32_32x32x16_bf16 v[0:15], v[34:37], v[64:67], v[0:15]
	s_waitcnt lgkmcnt(0)
	v_mfma_f32_32x32x16_bf16 v[0:15], v[38:41], v[72:75], v[0:15]
	ds_read_b64 v[38:39], v43 offset:800
	ds_read_b64 v[40:41], v43 offset:816
	s_waitcnt lgkmcnt(0)
	v_mfma_f32_32x32x16_bf16 v[16:31], v[38:41], v[64:67], v[16:31]
	ds_read_b64 v[38:39], v42 offset:1344
	ds_read_b64 v[40:41], v42 offset:1360
	v_mfma_f32_32x32x16_bf16 v[16:31], v[34:37], v[72:75], v[16:31]
	ds_read_b64 v[34:35], v48 offset:320
	ds_read_b64 v[36:37], v48 offset:336
	s_waitcnt lgkmcnt(0)
	v_mfma_f32_32x32x16_bf16 v[0:15], v[34:37], v[80:83], v[0:15]
	v_mfma_f32_32x32x16_bf16 v[0:15], v[38:41], v[84:87], v[0:15]
	ds_read_b64 v[38:39], v43 offset:832
	ds_read_b64 v[40:41], v43 offset:848
	s_waitcnt lgkmcnt(0)
	v_mfma_f32_32x32x16_bf16 v[16:31], v[38:41], v[80:83], v[16:31]
	ds_read_b64 v[38:39], v42 offset:1376
	ds_read_b64 v[40:41], v42 offset:1392
	v_mfma_f32_32x32x16_bf16 v[16:31], v[34:37], v[84:87], v[16:31]
	ds_read_b64 v[34:35], v48 offset:352
	ds_read_b64 v[36:37], v48 offset:368
	s_waitcnt lgkmcnt(0)
	v_mfma_f32_32x32x16_bf16 v[0:15], v[34:37], v[88:91], v[0:15]
	v_mfma_f32_32x32x16_bf16 v[0:15], v[38:41], v[92:95], v[0:15]
	ds_read_b64 v[38:39], v43 offset:864
	ds_read_b64 v[40:41], v43 offset:880
	s_waitcnt lgkmcnt(0)
	v_mfma_f32_32x32x16_bf16 v[16:31], v[38:41], v[88:91], v[16:31]
	s_nop 8
	v_fma_f32 v0, v105, v0, v104
	v_mfma_f32_32x32x16_bf16 v[16:31], v[34:37], v[92:95], v[16:31]
	s_nop 11
	v_mul_f32_e32 v16, v105, v16
	v_cvt_pk_bf16_f32 v0, v0, v16
	global_store_dword v[32:33], v0, off
	v_fma_f32 v0, v105, v1, v104
	v_mul_f32_e32 v1, v105, v17
	v_cvt_pk_bf16_f32 v0, v0, v1
	global_store_dword v[32:33], v0, off offset:256
	v_fma_f32 v0, v105, v2, v104
	v_mul_f32_e32 v1, v105, v18
	v_cvt_pk_bf16_f32 v0, v0, v1
	global_store_dword v[32:33], v0, off offset:512
	v_fma_f32 v0, v105, v3, v104
	v_mul_f32_e32 v1, v105, v19
	v_cvt_pk_bf16_f32 v0, v0, v1
	global_store_dword v[32:33], v0, off offset:768
	v_fma_f32 v0, v105, v4, v104
	v_mul_f32_e32 v1, v105, v20
	v_cvt_pk_bf16_f32 v0, v0, v1
	global_store_dword v[32:33], v0, off offset:2048
	v_fma_f32 v0, v105, v5, v104
	v_mul_f32_e32 v1, v105, v21
	v_cvt_pk_bf16_f32 v0, v0, v1
	global_store_dword v[32:33], v0, off offset:2304
	v_fma_f32 v0, v105, v6, v104
	v_mul_f32_e32 v1, v105, v22
	v_cvt_pk_bf16_f32 v0, v0, v1
	global_store_dword v[32:33], v0, off offset:2560
	v_fma_f32 v0, v105, v7, v104
	v_mul_f32_e32 v1, v105, v23
	v_cvt_pk_bf16_f32 v0, v0, v1
	global_store_dword v[32:33], v0, off offset:2816
	v_fma_f32 v0, v105, v8, v104
	v_mul_f32_e32 v1, v105, v24
	v_cvt_pk_bf16_f32 v2, v0, v1
	v_add_co_u32_e32 v0, vcc, s38, v106
	v_mul_f32_e32 v3, v105, v25
	s_nop 0
	v_addc_co_u32_e32 v1, vcc, 0, v107, vcc
	global_store_dword v[0:1], v2, off
	v_fma_f32 v2, v105, v9, v104
	v_cvt_pk_bf16_f32 v2, v2, v3
	global_store_dword v[0:1], v2, off offset:256
	v_fma_f32 v2, v105, v10, v104
	v_mul_f32_e32 v3, v105, v26
	v_cvt_pk_bf16_f32 v2, v2, v3
	global_store_dword v[0:1], v2, off offset:512
	v_fma_f32 v2, v105, v11, v104
	v_mul_f32_e32 v3, v105, v27
	v_cvt_pk_bf16_f32 v2, v2, v3
	global_store_dword v[0:1], v2, off offset:768
	v_fma_f32 v2, v105, v12, v104
	v_mul_f32_e32 v3, v105, v28
	v_cvt_pk_bf16_f32 v2, v2, v3
	global_store_dword v[0:1], v2, off offset:2048
	v_fma_f32 v2, v105, v13, v104
	v_mul_f32_e32 v3, v105, v29
	v_cvt_pk_bf16_f32 v2, v2, v3
	global_store_dword v[0:1], v2, off offset:2304
	v_fma_f32 v2, v105, v14, v104
	v_mul_f32_e32 v3, v105, v30
	v_cvt_pk_bf16_f32 v2, v2, v3
	global_store_dword v[0:1], v2, off offset:2560
	v_mul_f32_e32 v2, v105, v31
	v_fmac_f32_e32 v104, v105, v15
	v_cvt_pk_bf16_f32 v2, v104, v2
	global_store_dword v[0:1], v2, off offset:2816
	s_barrier
	s_cbranch_scc0 .LBB0_362

.LBB0_2016:
	s_or_b64 exec, exec, s[8:9]
	v_mov_b32_e32 v4, s51
	s_waitcnt lgkmcnt(0)
	s_barrier
	ds_read2_b32 v[12:13], v4 offset1:4
	ds_read_b64_tr_b16 v[0:1], v165
	ds_read_b64_tr_b16 v[2:3], v165 offset:768
	ds_read2_b32 v[14:15], v4 offset0:8 offset1:12
	ds_read2_b32 v[102:103], v4 offset0:16 offset1:20
	ds_read2_b32 v[100:101], v4 offset0:24 offset1:28
	ds_read_b64 v[4:5], v166
	ds_read_b64 v[6:7], v166 offset:8
	s_or_b32 s8, s55, s50
	s_lshl_b32 s9, s54, 9
	v_add_u32_e32 v72, 0x2200, v166
	ds_read_b64 v[8:9], v72
	ds_read_b64 v[10:11], v72 offset:8
	s_or_b32 s8, s8, s9
	s_add_i32 s10, s8, 0x400
	s_ashr_i32 s11, s10, 31
	s_lshl_b64 s[10:11], s[10:11], 2
	s_waitcnt lgkmcnt(2)
	v_mfma_f32_32x32x16_bf16 v[18:33], v[0:3], v[4:7], 0
	s_add_u32 s10, s18, s10
	s_addc_u32 s11, s19, s11
	global_load_dword v104, v93, s[10:11]
	v_add_u32_e32 v78, 0x2220, v166
	v_add_u32_e32 v79, 0x2240, v166
	v_add_u32_e32 v86, 0x2260, v166
	s_waitcnt lgkmcnt(0)
	v_mfma_f32_32x32x16_bf16 v[34:49], v[0:3], v[8:11], 0
	ds_read_b64_tr_b16 v[0:1], v165 offset:3072
	ds_read_b64_tr_b16 v[2:3], v165 offset:3840
	ds_read_b64 v[4:5], v166 offset:32
	ds_read_b64 v[6:7], v166 offset:40
	ds_read_b64 v[8:9], v78
	ds_read_b64 v[10:11], v78 offset:8
	v_add_u32_e32 v178, 0x4000, v167
	v_add_u32_e32 v179, 0x2000, v167
	s_ashr_i32 s9, s8, 31
	s_lshl_b64 s[8:9], s[8:9], 14
	s_waitcnt lgkmcnt(2)
	v_mfma_f32_32x32x16_bf16 v[18:33], v[0:3], v[4:7], v[18:33]
	s_waitcnt lgkmcnt(0)
	v_mfma_f32_32x32x16_bf16 v[34:49], v[0:3], v[8:11], v[34:49]
	ds_read_b64_tr_b16 v[0:1], v165 offset:6144
	ds_read_b64_tr_b16 v[2:3], v165 offset:6912
	ds_read_b64 v[4:5], v166 offset:64
	ds_read_b64 v[6:7], v166 offset:72
	ds_read_b64 v[8:9], v79
	ds_read_b64 v[10:11], v79 offset:8
	s_waitcnt lgkmcnt(2)
	v_mfma_f32_32x32x16_bf16 v[18:33], v[0:3], v[4:7], v[18:33]
	v_add_f32_e32 v4, 0, v12
	v_add_f32_e32 v12, v4, v13
	ds_read_b64_tr_b16 v[4:5], v165 offset:9216
	ds_read_b64_tr_b16 v[6:7], v165 offset:9984
	s_waitcnt lgkmcnt(2)
	v_mfma_f32_32x32x16_bf16 v[34:49], v[0:3], v[8:11], v[34:49]
	v_add_f32_e32 v0, v12, v14
	v_add_f32_e32 v8, v0, v15
	ds_read_b64 v[0:1], v166 offset:96
	ds_read_b64 v[2:3], v166 offset:104
	v_add_f32_e32 v102, v8, v102
	ds_read_b64 v[8:9], v86
	ds_read_b64 v[10:11], v86 offset:8
	s_waitcnt lgkmcnt(0)
	v_mfma_f32_32x32x16_bf16 v[34:49], v[4:7], v[8:11], v[34:49]
	v_mfma_f32_32x32x16_bf16 v[18:33], v[4:7], v[0:3], v[18:33]
	ds_read_b32 v2, v126
	ds_read_b32 v3, v127
	ds_read_b32 v12, v128
	ds_read_b32 v13, v129
	ds_read_b32 v14, v130
	ds_read_b32 v15, v131
	ds_read_b32 v16, v132
	ds_read_b32 v17, v133
	s_waitcnt lgkmcnt(6)
	v_cvt_f32_f16_e32 v1, v3
	v_cvt_f32_f16_e32 v0, v2
	v_cvt_f32_f16_sdwa v3, v3 dst_sel:DWORD dst_unused:UNUSED_PAD src0_sel:WORD_1
	v_cvt_f32_f16_sdwa v2, v2 dst_sel:DWORD dst_unused:UNUSED_PAD src0_sel:WORD_1
	s_waitcnt lgkmcnt(4)
	v_cvt_f32_f16_sdwa v7, v13 dst_sel:DWORD dst_unused:UNUSED_PAD src0_sel:WORD_1
	v_cvt_f32_f16_sdwa v6, v12 dst_sel:DWORD dst_unused:UNUSED_PAD src0_sel:WORD_1
	v_pk_mul_f32 v[4:5], v[34:35], v[2:3]
	s_nop 0
	v_pk_fma_f32 v[50:51], v[18:19], v[0:1], v[4:5] neg_lo:[0,0,1] neg_hi:[0,0,1]
	v_cvt_f32_f16_e32 v5, v13
	v_cvt_f32_f16_e32 v4, v12
	v_pk_mul_f32 v[2:3], v[18:19], v[2:3]
	s_nop 0
	v_pk_fma_f32 v[52:53], v[34:35], v[0:1], v[2:3]
	v_pk_mul_f32 v[0:1], v[36:37], v[6:7]
	s_waitcnt lgkmcnt(2)
	v_cvt_f32_f16_sdwa v3, v15 dst_sel:DWORD dst_unused:UNUSED_PAD src0_sel:WORD_1
	v_cvt_f32_f16_sdwa v2, v14 dst_sel:DWORD dst_unused:UNUSED_PAD src0_sel:WORD_1
	v_pk_fma_f32 v[54:55], v[20:21], v[4:5], v[0:1] neg_lo:[0,0,1] neg_hi:[0,0,1]
	v_cvt_f32_f16_e32 v1, v15
	v_cvt_f32_f16_e32 v0, v14
	v_pk_mul_f32 v[6:7], v[20:21], v[6:7]
	s_nop 0
	v_pk_fma_f32 v[56:57], v[36:37], v[4:5], v[6:7]
	v_pk_mul_f32 v[4:5], v[38:39], v[2:3]
	s_waitcnt lgkmcnt(0)
	v_cvt_f32_f16_sdwa v7, v17 dst_sel:DWORD dst_unused:UNUSED_PAD src0_sel:WORD_1
	v_cvt_f32_f16_sdwa v6, v16 dst_sel:DWORD dst_unused:UNUSED_PAD src0_sel:WORD_1
	v_pk_fma_f32 v[58:59], v[22:23], v[0:1], v[4:5] neg_lo:[0,0,1] neg_hi:[0,0,1]
	v_cvt_f32_f16_e32 v5, v17
	v_cvt_f32_f16_e32 v4, v16
	v_pk_mul_f32 v[2:3], v[22:23], v[2:3]
	s_nop 0
	v_pk_fma_f32 v[60:61], v[38:39], v[0:1], v[2:3]
	v_pk_mul_f32 v[0:1], v[40:41], v[6:7]
	v_pk_mul_f32 v[6:7], v[24:25], v[6:7]
	v_pk_fma_f32 v[62:63], v[24:25], v[4:5], v[0:1] neg_lo:[0,0,1] neg_hi:[0,0,1]
	ds_read_b32 v0, v134
	ds_read_b32 v2, v135
	ds_read_b32 v8, v136
	ds_read_b32 v9, v137
	ds_read_b32 v10, v138
	ds_read_b32 v11, v139
	ds_read_b32 v74, v140
	ds_read_b32 v75, v141
	s_waitcnt lgkmcnt(6)
	v_cvt_f32_f16_e32 v1, v2
	v_cvt_f32_f16_sdwa v3, v2 dst_sel:DWORD dst_unused:UNUSED_PAD src0_sel:WORD_1
	v_cvt_f32_f16_sdwa v2, v0 dst_sel:DWORD dst_unused:UNUSED_PAD src0_sel:WORD_1
	v_cvt_f32_f16_e32 v0, v0
	v_pk_fma_f32 v[64:65], v[40:41], v[4:5], v[6:7]
	s_waitcnt lgkmcnt(4)
	v_cvt_f32_f16_sdwa v7, v9 dst_sel:DWORD dst_unused:UNUSED_PAD src0_sel:WORD_1
	v_pk_mul_f32 v[4:5], v[42:43], v[2:3]
	v_cvt_f32_f16_sdwa v6, v8 dst_sel:DWORD dst_unused:UNUSED_PAD src0_sel:WORD_1
	v_pk_fma_f32 v[66:67], v[26:27], v[0:1], v[4:5] neg_lo:[0,0,1] neg_hi:[0,0,1]
	v_cvt_f32_f16_e32 v5, v9
	v_cvt_f32_f16_e32 v4, v8
	v_pk_mul_f32 v[2:3], v[26:27], v[2:3]
	ds_read_b64_tr_b16 v[16:17], v165 offset:64
	ds_read_b64_tr_b16 v[18:19], v165 offset:832
	v_pk_fma_f32 v[68:69], v[42:43], v[0:1], v[2:3]
	v_pk_mul_f32 v[0:1], v[44:45], v[6:7]
	s_waitcnt lgkmcnt(4)
	v_cvt_f32_f16_sdwa v27, v11 dst_sel:DWORD dst_unused:UNUSED_PAD src0_sel:WORD_1
	v_pk_fma_f32 v[70:71], v[28:29], v[4:5], v[0:1] neg_lo:[0,0,1] neg_hi:[0,0,1]
	v_pk_mul_f32 v[0:1], v[28:29], v[6:7]
	v_cvt_f32_f16_sdwa v26, v10 dst_sel:DWORD dst_unused:UNUSED_PAD src0_sel:WORD_1
	v_pk_fma_f32 v[80:81], v[44:45], v[4:5], v[0:1]
	ds_read_b64 v[0:1], v166
	ds_read_b64 v[2:3], v166 offset:8
	ds_read_b64 v[20:21], v72
	ds_read_b64 v[22:23], v72 offset:8
	v_cvt_f32_f16_e32 v25, v11
	v_cvt_f32_f16_e32 v24, v10
	v_pk_mul_f32 v[28:29], v[46:47], v[26:27]
	v_pk_mul_f32 v[26:27], v[30:31], v[26:27]
	s_waitcnt lgkmcnt(2)
	v_mfma_f32_32x32x16_bf16 v[0:15], v[16:19], v[0:3], 0
	v_fma_f32 v82, v30, v24, -v28
	v_fma_f32 v83, v31, v25, -v29
	v_fma_f32 v46, v46, v24, v26
	v_fma_f32 v47, v47, v25, v27
	ds_read_b64_tr_b16 v[34:35], v165 offset:3136
	ds_read_b64_tr_b16 v[36:37], v165 offset:3904
	ds_read_b64 v[38:39], v166 offset:32
	ds_read_b64 v[40:41], v166 offset:40
	ds_read_b64 v[42:43], v78
	ds_read_b64 v[44:45], v78 offset:8
	v_cvt_f32_f16_sdwa v73, v75 dst_sel:DWORD dst_unused:UNUSED_PAD src0_sel:WORD_1
	s_waitcnt lgkmcnt(6)
	v_mfma_f32_32x32x16_bf16 v[16:31], v[16:19], v[20:23], 0
	v_cvt_f32_f16_sdwa v72, v74 dst_sel:DWORD dst_unused:UNUSED_PAD src0_sel:WORD_1
	v_cvt_f32_f16_e32 v75, v75
	v_cvt_f32_f16_e32 v74, v74
	v_mul_f32_e64 v76, v48, v72
	v_mul_f32_e64 v77, v49, v73
	v_cvt_pk_bf16_f32 v68, v68, v69
	v_pk_fma_f32 v[84:85], v[32:33], v[74:75], v[76:77] neg_lo:[0,0,1] neg_hi:[0,0,1]
	s_waitcnt lgkmcnt(0)
	v_mfma_f32_32x32x16_bf16 v[16:31], v[34:37], v[42:45], v[16:31]
	v_mul_f32_e64 v32, v32, v72
	v_mul_f32_e64 v33, v33, v73
	v_cvt_pk_bf16_f32 v73, v54, v55
	v_fma_f32 v48, v48, v74, v32
	v_fma_f32 v49, v49, v75, v33
	v_cvt_pk_bf16_f32 v74, v58, v59
	v_cvt_pk_bf16_f32 v69, v80, v81
	v_cvt_pk_bf16_f32 v76, v52, v53
	v_cvt_pk_bf16_f32 v72, v50, v51
	v_mfma_f32_32x32x16_bf16 v[0:15], v[34:37], v[38:41], v[0:15]
	ds_read_b64_tr_b16 v[38:39], v165 offset:6208
	ds_read_b64_tr_b16 v[40:41], v165 offset:6976
	ds_read_b64 v[32:33], v166 offset:64
	ds_read_b64 v[34:35], v166 offset:72
	ds_read_b64 v[42:43], v79
	ds_read_b64 v[44:45], v79 offset:8
	v_cvt_pk_bf16_f32 v79, v64, v65
	v_cvt_pk_bf16_f32 v64, v66, v67
	v_cvt_pk_bf16_f32 v66, v82, v83
	s_waitcnt lgkmcnt(0)
	v_mfma_f32_32x32x16_bf16 v[16:31], v[38:41], v[42:45], v[16:31]
	v_cvt_pk_bf16_f32 v67, v84, v85
	v_cvt_pk_bf16_f32 v75, v62, v63
	v_cvt_pk_bf16_f32 v77, v56, v57
	v_cvt_pk_bf16_f32 v65, v70, v71
	v_cvt_pk_bf16_f32 v71, v48, v49
	v_cvt_pk_bf16_f32 v70, v46, v47
	v_cvt_pk_bf16_f32 v78, v60, v61
	v_mfma_f32_32x32x16_bf16 v[0:15], v[38:41], v[32:35], v[0:15]
	ds_read_b64_tr_b16 v[32:33], v165 offset:9280
	ds_read_b64_tr_b16 v[34:35], v165 offset:10048
	ds_read_b64 v[36:37], v166 offset:96
	ds_read_b64 v[38:39], v166 offset:104
	ds_read_b64 v[40:41], v86
	ds_read_b64 v[42:43], v86 offset:8
	s_waitcnt lgkmcnt(0)
	v_mfma_f32_32x32x16_bf16 v[16:31], v[32:35], v[40:43], v[16:31]
	v_mfma_f32_32x32x16_bf16 v[0:15], v[32:35], v[36:39], v[0:15]
	ds_read_b32 v36, v142
	ds_read_b32 v37, v143
	ds_read_b32 v54, v144
	ds_read_b32 v55, v145
	ds_read_b32 v58, v146
	ds_read_b32 v59, v147
	ds_read_b32 v105, v148
	ds_read_b32 v176, v149
	ds_read_b64 v[80:81], v167
	ds_read_b64 v[82:83], v167 offset:16
	s_waitcnt lgkmcnt(8)
	v_cvt_f32_f16_e32 v53, v37
	v_cvt_f32_f16_e32 v52, v36
	v_cvt_f32_f16_sdwa v37, v37 dst_sel:DWORD dst_unused:UNUSED_PAD src0_sel:WORD_1
	v_cvt_f32_f16_sdwa v36, v36 dst_sel:DWORD dst_unused:UNUSED_PAD src0_sel:WORD_1
	s_waitcnt lgkmcnt(6)
	v_cvt_f32_f16_sdwa v57, v55 dst_sel:DWORD dst_unused:UNUSED_PAD src0_sel:WORD_1
	ds_read_b64 v[48:49], v178 offset:1024
	ds_read_b64 v[50:51], v178 offset:1040
	v_cvt_f32_f16_sdwa v56, v54 dst_sel:DWORD dst_unused:UNUSED_PAD src0_sel:WORD_1
	v_pk_mul_f32 v[32:33], v[16:17], v[36:37]
	s_waitcnt lgkmcnt(6)
	v_cvt_f32_f16_e32 v169, v59
	v_pk_fma_f32 v[84:85], v[0:1], v[52:53], v[32:33] neg_lo:[0,0,1] neg_hi:[0,0,1]
	v_pk_mul_f32 v[0:1], v[0:1], v[36:37]
	s_waitcnt lgkmcnt(2)
	v_mfma_f32_32x32x16_bf16 v[32:47], v[80:83], v[72:75], 0
	v_fma_f32 v86, v16, v52, v0
	v_fma_f32 v87, v17, v53, v1
	v_cvt_f32_f16_e32 v1, v55
	v_cvt_f32_f16_e32 v0, v54
	ds_read_b64 v[52:53], v179 offset:512
	ds_read_b64 v[54:55], v179 offset:528
	v_pk_mul_f32 v[16:17], v[18:19], v[56:57]
	ds_read_b32 v180, v150
	ds_read_b32 v181, v151
	ds_read_b32 v182, v152
	ds_read_b32 v183, v153
	ds_read_b32 v184, v154
	ds_read_b32 v185, v155
	ds_read_b32 v186, v156
	ds_read_b32 v187, v157
	v_pk_fma_f32 v[88:89], v[2:3], v[0:1], v[16:17] neg_lo:[0,0,1] neg_hi:[0,0,1]
	v_pk_mul_f32 v[2:3], v[2:3], v[56:57]
	s_waitcnt lgkmcnt(10)
	v_mfma_f32_32x32x16_bf16 v[32:47], v[48:51], v[76:79], v[32:47]
	v_fma_f32 v90, v18, v0, v2
	v_fma_f32 v91, v19, v1, v3
	ds_read_b64 v[0:1], v167 offset:32
	ds_read_b64 v[2:3], v167 offset:48
	v_cvt_f32_f16_e32 v168, v58
	v_cvt_f32_f16_sdwa v171, v59 dst_sel:DWORD dst_unused:UNUSED_PAD src0_sel:WORD_1
	v_cvt_f32_f16_sdwa v170, v58 dst_sel:DWORD dst_unused:UNUSED_PAD src0_sel:WORD_1
	v_cvt_f32_f16_e32 v175, v176
	v_cvt_f32_f16_sdwa v177, v176 dst_sel:DWORD dst_unused:UNUSED_PAD src0_sel:WORD_1
	s_waitcnt lgkmcnt(10)
	v_mfma_f32_32x32x16_bf16 v[48:63], v[52:55], v[72:75], 0
	v_mul_f32_e64 v16, v20, v170
	v_mul_f32_e64 v17, v21, v171
	v_cvt_f32_f16_sdwa v176, v105 dst_sel:DWORD dst_unused:UNUSED_PAD src0_sel:WORD_1
	v_fma_f32 v172, v4, v168, -v16
	v_fma_f32 v173, v5, v169, -v17
	ds_read_b64 v[16:17], v178 offset:1056
	ds_read_b64 v[18:19], v178 offset:1072
	v_cvt_f32_f16_e32 v174, v105
	v_pk_mul_f32 v[4:5], v[4:5], v[170:171]
	s_waitcnt lgkmcnt(10)
	v_cvt_f32_f16_sdwa v171, v181 dst_sel:DWORD dst_unused:UNUSED_PAD src0_sel:WORD_1
	v_mfma_f32_32x32x16_bf16 v[48:63], v[80:83], v[76:79], v[48:63]
	ds_read_b64 v[80:81], v179 offset:544
	ds_read_b64 v[82:83], v179 offset:560
	v_fma_f32 v20, v20, v168, v4
	v_fma_f32 v21, v21, v169, v5
	v_mul_f32_e64 v4, v22, v176
	v_mul_f32_e64 v5, v23, v177
	v_cvt_f32_f16_sdwa v170, v180 dst_sel:DWORD dst_unused:UNUSED_PAD src0_sel:WORD_1
	v_pk_fma_f32 v[168:169], v[6:7], v[174:175], v[4:5] neg_lo:[0,0,1] neg_hi:[0,0,1]
	v_cvt_f32_f16_e32 v5, v181
	v_cvt_f32_f16_e32 v4, v180
	s_waitcnt lgkmcnt(4)
	v_mfma_f32_32x32x16_bf16 v[32:47], v[0:3], v[64:67], v[32:47]
	v_mul_f32_e64 v6, v6, v176
	v_mul_f32_e64 v7, v7, v177
	s_waitcnt lgkmcnt(2)
	v_mfma_f32_32x32x16_bf16 v[32:47], v[16:19], v[68:71], v[32:47]
	v_fma_f32 v16, v22, v174, v6
	v_fma_f32 v17, v23, v175, v7
	v_mul_f32_e64 v6, v24, v170
	v_mul_f32_e64 v7, v25, v171
	v_fma_f32 v22, v8, v4, -v6
	v_fma_f32 v23, v9, v5, -v7
	v_pk_mul_f32 v[6:7], v[8:9], v[170:171]
	v_cvt_f32_f16_sdwa v171, v183 dst_sel:DWORD dst_unused:UNUSED_PAD src0_sel:WORD_1
	v_pk_fma_f32 v[8:9], v[24:25], v[4:5], v[6:7]
	s_waitcnt lgkmcnt(0)
	v_mfma_f32_32x32x16_bf16 v[48:63], v[80:83], v[64:67], v[48:63]
	ds_read_b64 v[4:5], v167 offset:64
	ds_read_b64 v[6:7], v167 offset:80
	v_cvt_f32_f16_sdwa v170, v182 dst_sel:DWORD dst_unused:UNUSED_PAD src0_sel:WORD_1
	v_cvt_f32_f16_e32 v25, v183
	v_cvt_f32_f16_e32 v24, v182
	v_cvt_pk_bf16_f32 v80, v84, v85
	v_cvt_pk_bf16_f32 v81, v88, v89
	v_cvt_pk_bf16_f32 v82, v172, v173
	v_mfma_f32_32x32x16_bf16 v[48:63], v[0:3], v[68:71], v[48:63]
	v_mul_f32_e64 v0, v26, v170
	v_mul_f32_e64 v1, v27, v171
	v_cvt_pk_bf16_f32 v83, v168, v169
	v_fma_f32 v174, v10, v24, -v0
	v_fma_f32 v175, v11, v25, -v1
	ds_read_b64 v[0:1], v178 offset:1088
	ds_read_b64 v[2:3], v178 offset:1104
	v_cvt_pk_bf16_f32 v89, v90, v91
	v_cvt_pk_bf16_f32 v91, v16, v17
	ds_read_b64 v[16:17], v179 offset:576
	ds_read_b64 v[18:19], v179 offset:592
	s_waitcnt lgkmcnt(4)
	v_mfma_f32_32x32x16_bf16 v[32:47], v[4:7], v[80:83], v[32:47]
	v_cvt_f32_f16_sdwa v169, v185 dst_sel:DWORD dst_unused:UNUSED_PAD src0_sel:WORD_1
	v_cvt_f32_f16_sdwa v168, v184 dst_sel:DWORD dst_unused:UNUSED_PAD src0_sel:WORD_1
	v_cvt_f32_f16_e32 v85, v185
	v_cvt_f32_f16_e32 v84, v184
	v_cvt_pk_bf16_f32 v88, v86, v87
	v_cvt_pk_bf16_f32 v90, v20, v21
	s_waitcnt lgkmcnt(0)
	v_mfma_f32_32x32x16_bf16 v[48:63], v[16:19], v[80:83], v[48:63]
	v_cvt_f32_f16_sdwa v19, v187 dst_sel:DWORD dst_unused:UNUSED_PAD src0_sel:WORD_1
	v_cvt_f32_f16_sdwa v18, v186 dst_sel:DWORD dst_unused:UNUSED_PAD src0_sel:WORD_1
	v_cvt_f32_f16_e32 v17, v187
	v_cvt_f32_f16_e32 v16, v186
	v_mfma_f32_32x32x16_bf16 v[32:47], v[0:3], v[88:91], v[32:47]
	v_mul_f32_e64 v0, v10, v170
	v_mul_f32_e64 v1, v11, v171
	v_fma_f32 v10, v26, v24, v0
	v_fma_f32 v11, v27, v25, v1
	v_mul_f32_e64 v0, v28, v168
	v_mul_f32_e64 v1, v29, v169
	v_pk_fma_f32 v[20:21], v[12:13], v[84:85], v[0:1] neg_lo:[0,0,1] neg_hi:[0,0,1]
	v_pk_mul_f32 v[0:1], v[12:13], v[168:169]
	v_cvt_pk_bf16_f32 v168, v8, v9
	v_pk_fma_f32 v[12:13], v[28:29], v[84:85], v[0:1]
	ds_read_b64 v[0:1], v167 offset:96
	ds_read_b64 v[2:3], v167 offset:112
	v_cvt_pk_bf16_f32 v169, v10, v11
	ds_read_b64 v[8:9], v179 offset:608
	ds_read_b64 v[10:11], v179 offset:624
	v_mfma_f32_32x32x16_bf16 v[48:63], v[4:7], v[88:91], v[48:63]
	v_mul_f32_e64 v4, v30, v18
	v_mul_f32_e64 v5, v31, v19
	v_cvt_pk_bf16_f32 v84, v22, v23
	v_fma_f32 v4, v14, v16, -v4
	v_fma_f32 v5, v15, v17, -v5
	v_cvt_pk_bf16_f32 v85, v174, v175
	v_cvt_pk_bf16_f32 v86, v20, v21
	v_cvt_pk_bf16_f32 v87, v4, v5
	ds_read_b64 v[4:5], v178 offset:1120
	ds_read_b64 v[6:7], v178 offset:1136
	v_pk_mul_f32 v[14:15], v[14:15], v[18:19]
	s_waitcnt lgkmcnt(4)
	v_mfma_f32_32x32x16_bf16 v[32:47], v[0:3], v[84:87], v[32:47]
	v_fma_f32 v14, v30, v16, v14
	v_fma_f32 v15, v31, v17, v15
	v_cvt_pk_bf16_f32 v170, v12, v13
	v_cvt_pk_bf16_f32 v171, v14, v15
	s_waitcnt lgkmcnt(2)
	v_mfma_f32_32x32x16_bf16 v[48:63], v[8:11], v[84:87], v[48:63]
	s_waitcnt lgkmcnt(0)
	v_mfma_f32_32x32x16_bf16 v[32:47], v[4:7], v[168:171], v[32:47]
	v_add_f32_e32 v4, v102, v103
	v_add_f32_e32 v4, v4, v100
	v_add_f32_e32 v4, v4, v101
	v_add_f32_e32 v4, 0x358637bd, v4
	v_mul_f32_e32 v5, 0x4b800000, v4
	v_cmp_gt_f32_e32 vcc, s44, v4
	v_lshl_add_u64 v[102:103], v[98:99], 0, s[8:9]
	v_mfma_f32_32x32x16_bf16 v[48:63], v[0:3], v[168:171], v[48:63]
	v_cndmask_b32_e32 v4, v4, v5, vcc
	v_rsq_f32_e32 v4, v4
	s_add_i32 s8, s49, 0x100
	s_cmp_lt_i32 s49, 0
	s_mov_b32 s49, s8
	v_mul_f32_e32 v5, 0x45800000, v4
	v_cndmask_b32_e32 v105, v4, v5, vcc
	s_waitcnt vmcnt(0)
	v_pk_mul_f32 v[100:101], v[104:105], s[26:27] op_sel_hi:[1,0]
	s_nop 0
	v_fma_f32 v0, v101, v32, v100
	s_nop 0
	v_mul_f32_e32 v1, v101, v48
	v_cvt_pk_bf16_f32 v0, v0, v1
	global_store_dword v[102:103], v0, off
	v_fma_f32 v0, v101, v33, v100
	v_mul_f32_e32 v1, v101, v49
	v_cvt_pk_bf16_f32 v0, v0, v1
	global_store_dword v[102:103], v0, off offset:256
	v_fma_f32 v0, v101, v34, v100
	v_mul_f32_e32 v1, v101, v50
	v_cvt_pk_bf16_f32 v0, v0, v1
	global_store_dword v[102:103], v0, off offset:512
	v_fma_f32 v0, v101, v35, v100
	v_mul_f32_e32 v1, v101, v51
	v_cvt_pk_bf16_f32 v0, v0, v1
	global_store_dword v[102:103], v0, off offset:768
	v_fma_f32 v0, v101, v36, v100
	v_mul_f32_e32 v1, v101, v52
	v_cvt_pk_bf16_f32 v0, v0, v1
	global_store_dword v[102:103], v0, off offset:2048
	v_fma_f32 v0, v101, v37, v100
	v_mul_f32_e32 v1, v101, v53
	v_cvt_pk_bf16_f32 v0, v0, v1
	global_store_dword v[102:103], v0, off offset:2304
	v_fma_f32 v0, v101, v38, v100
	v_mul_f32_e32 v1, v101, v54
	v_cvt_pk_bf16_f32 v0, v0, v1
	global_store_dword v[102:103], v0, off offset:2560
	v_fma_f32 v0, v101, v39, v100
	v_mul_f32_e32 v1, v101, v55
	v_cvt_pk_bf16_f32 v0, v0, v1
	global_store_dword v[102:103], v0, off offset:2816
	v_fma_f32 v0, v101, v40, v100
	v_add_u32_e32 v40, 0x1000, v167
	ds_read_b64 v[32:33], v40 offset:256
	ds_read_b64 v[34:35], v40 offset:272
	v_add_co_u32_e32 v36, vcc, s2, v102
	v_mul_f32_e32 v1, v101, v56
	s_nop 0
	v_addc_co_u32_e32 v37, vcc, 0, v103, vcc
	v_add_co_u32_e32 v48, vcc, s45, v102
	v_cvt_pk_bf16_f32 v0, v0, v1
	s_nop 0
	v_addc_co_u32_e32 v49, vcc, 0, v103, vcc
	global_store_dword v[48:49], v0, off offset:-4096
	v_fma_f32 v0, v101, v41, v100
	v_mul_f32_e32 v1, v101, v57
	v_cvt_pk_bf16_f32 v0, v0, v1
	global_store_dword v[36:37], v0, off offset:256
	v_fma_f32 v0, v101, v42, v100
	v_mul_f32_e32 v1, v101, v58
	v_add_u32_e32 v41, 0x5000, v167
	v_cvt_pk_bf16_f32 v0, v0, v1
	ds_read_b64 v[16:17], v41 offset:1280
	ds_read_b64 v[18:19], v41 offset:1296
	global_store_dword v[36:37], v0, off offset:512
	v_fma_f32 v20, v101, v43, v100
	s_waitcnt lgkmcnt(2)
	v_mfma_f32_32x32x16_bf16 v[0:15], v[32:35], v[72:75], 0
	v_mul_f32_e32 v21, v101, v59
	v_cvt_pk_bf16_f32 v20, v20, v21
	v_add_u32_e32 v42, 0x3000, v167
	global_store_dword v[36:37], v20, off offset:768
	ds_read_b64 v[20:21], v42 offset:768
	ds_read_b64 v[22:23], v42 offset:784
	v_fma_f32 v24, v101, v44, v100
	v_mul_f32_e32 v25, v101, v60
	s_waitcnt lgkmcnt(2)
	v_mfma_f32_32x32x16_bf16 v[0:15], v[16:19], v[76:79], v[0:15]
	v_cvt_pk_bf16_f32 v16, v24, v25
	global_store_dword v[36:37], v16, off offset:2048
	v_fma_f32 v16, v101, v45, v100
	v_mul_f32_e32 v17, v101, v61
	v_cvt_pk_bf16_f32 v16, v16, v17
	global_store_dword v[36:37], v16, off offset:2304
	v_fma_f32 v38, v101, v46, v100
	s_waitcnt lgkmcnt(0)
	v_mfma_f32_32x32x16_bf16 v[16:31], v[20:23], v[72:75], 0
	v_mul_f32_e32 v39, v101, v62
	v_cvt_pk_bf16_f32 v38, v38, v39
	global_store_dword v[36:37], v38, off offset:2560
	v_fma_f32 v38, v101, v47, v100
	v_mul_f32_e32 v39, v101, v63
	v_cvt_pk_bf16_f32 v38, v38, v39
	global_store_dword v[36:37], v38, off offset:2816
	v_mfma_f32_32x32x16_bf16 v[16:31], v[32:35], v[76:79], v[16:31]
	ds_read_b64 v[32:33], v40 offset:288
	ds_read_b64 v[34:35], v40 offset:304
	ds_read_b64 v[36:37], v41 offset:1312
	ds_read_b64 v[38:39], v41 offset:1328
	s_waitcnt lgkmcnt(2)
	v_mfma_f32_32x32x16_bf16 v[0:15], v[32:35], v[64:67], v[0:15]
	s_waitcnt lgkmcnt(0)
	v_mfma_f32_32x32x16_bf16 v[0:15], v[36:39], v[68:71], v[0:15]
	ds_read_b64 v[36:37], v42 offset:800
	ds_read_b64 v[38:39], v42 offset:816
	s_waitcnt lgkmcnt(0)
	v_mfma_f32_32x32x16_bf16 v[16:31], v[36:39], v[64:67], v[16:31]
	ds_read_b64 v[36:37], v41 offset:1344
	ds_read_b64 v[38:39], v41 offset:1360
	v_mfma_f32_32x32x16_bf16 v[16:31], v[32:35], v[68:71], v[16:31]
	ds_read_b64 v[32:33], v40 offset:320
	ds_read_b64 v[34:35], v40 offset:336
	s_waitcnt lgkmcnt(0)
	v_mfma_f32_32x32x16_bf16 v[0:15], v[32:35], v[80:83], v[0:15]
	v_mfma_f32_32x32x16_bf16 v[0:15], v[36:39], v[88:91], v[0:15]
	ds_read_b64 v[36:37], v42 offset:832
	ds_read_b64 v[38:39], v42 offset:848
	s_waitcnt lgkmcnt(0)
	v_mfma_f32_32x32x16_bf16 v[16:31], v[36:39], v[80:83], v[16:31]
	ds_read_b64 v[36:37], v41 offset:1376
	ds_read_b64 v[38:39], v41 offset:1392
	v_mfma_f32_32x32x16_bf16 v[16:31], v[32:35], v[88:91], v[16:31]
	ds_read_b64 v[32:33], v40 offset:352
	ds_read_b64 v[34:35], v40 offset:368
	s_waitcnt lgkmcnt(0)
	v_mfma_f32_32x32x16_bf16 v[0:15], v[32:35], v[84:87], v[0:15]
	v_mfma_f32_32x32x16_bf16 v[0:15], v[36:39], v[168:171], v[0:15]
	ds_read_b64 v[36:37], v42 offset:864
	ds_read_b64 v[38:39], v42 offset:880
	s_waitcnt lgkmcnt(0)
	v_mfma_f32_32x32x16_bf16 v[16:31], v[36:39], v[84:87], v[16:31]
	s_nop 8
	v_fma_f32 v0, v101, v0, v100
	v_mfma_f32_32x32x16_bf16 v[16:31], v[32:35], v[168:171], v[16:31]
	s_nop 11
	v_mul_f32_e32 v16, v101, v16
	v_cvt_pk_bf16_f32 v0, v0, v16
	global_store_dword v[48:49], v0, off
	v_fma_f32 v0, v101, v1, v100
	v_mul_f32_e32 v1, v101, v17
	v_cvt_pk_bf16_f32 v0, v0, v1
	global_store_dword v[48:49], v0, off offset:256
	v_fma_f32 v0, v101, v2, v100
	v_mul_f32_e32 v1, v101, v18
	v_cvt_pk_bf16_f32 v0, v0, v1
	global_store_dword v[48:49], v0, off offset:512
	v_fma_f32 v0, v101, v3, v100
	v_mul_f32_e32 v1, v101, v19
	v_cvt_pk_bf16_f32 v0, v0, v1
	global_store_dword v[48:49], v0, off offset:768
	v_fma_f32 v0, v101, v4, v100
	v_mul_f32_e32 v1, v101, v20
	v_cvt_pk_bf16_f32 v0, v0, v1
	global_store_dword v[48:49], v0, off offset:2048
	v_fma_f32 v0, v101, v5, v100
	v_mul_f32_e32 v1, v101, v21
	v_cvt_pk_bf16_f32 v0, v0, v1
	global_store_dword v[48:49], v0, off offset:2304
	v_fma_f32 v0, v101, v6, v100
	v_mul_f32_e32 v1, v101, v22
	v_cvt_pk_bf16_f32 v0, v0, v1
	global_store_dword v[48:49], v0, off offset:2560
	v_fma_f32 v0, v101, v7, v100
	v_mul_f32_e32 v1, v101, v23
	v_cvt_pk_bf16_f32 v0, v0, v1
	global_store_dword v[48:49], v0, off offset:2816
	v_fma_f32 v0, v101, v8, v100
	v_mul_f32_e32 v1, v101, v24
	v_cvt_pk_bf16_f32 v2, v0, v1
	v_add_co_u32_e32 v0, vcc, s38, v102
	v_mul_f32_e32 v3, v101, v25
	s_nop 0
	v_addc_co_u32_e32 v1, vcc, 0, v103, vcc
	global_store_dword v[0:1], v2, off
	v_fma_f32 v2, v101, v9, v100
	v_cvt_pk_bf16_f32 v2, v2, v3
	global_store_dword v[0:1], v2, off offset:256
	v_fma_f32 v2, v101, v10, v100
	v_mul_f32_e32 v3, v101, v26
	v_cvt_pk_bf16_f32 v2, v2, v3
	global_store_dword v[0:1], v2, off offset:512
	v_fma_f32 v2, v101, v11, v100
	v_mul_f32_e32 v3, v101, v27
	v_cvt_pk_bf16_f32 v2, v2, v3
	global_store_dword v[0:1], v2, off offset:768
	v_fma_f32 v2, v101, v12, v100
	v_mul_f32_e32 v3, v101, v28
	v_cvt_pk_bf16_f32 v2, v2, v3
	global_store_dword v[0:1], v2, off offset:2048
	v_fma_f32 v2, v101, v13, v100
	v_mul_f32_e32 v3, v101, v29
	v_cvt_pk_bf16_f32 v2, v2, v3
	global_store_dword v[0:1], v2, off offset:2304
	v_fma_f32 v2, v101, v14, v100
	v_mul_f32_e32 v3, v101, v30
	v_cvt_pk_bf16_f32 v2, v2, v3
	global_store_dword v[0:1], v2, off offset:2560
	v_mul_f32_e32 v2, v101, v31
	v_fmac_f32_e32 v100, v101, v15
	v_cvt_pk_bf16_f32 v2, v100, v2
	global_store_dword v[0:1], v2, off offset:2816
	s_barrier
	s_cbranch_scc0 .LBB0_2010

.LBB0_2490:
	s_or_b64 exec, exec, s[8:9]
	v_mov_b32_e32 v4, s51
	s_waitcnt lgkmcnt(0)
	s_barrier
	ds_read2_b32 v[12:13], v4 offset1:4
	ds_read_b64_tr_b16 v[0:1], v165
	ds_read_b64_tr_b16 v[2:3], v165 offset:768
	ds_read2_b32 v[14:15], v4 offset0:8 offset1:12
	ds_read2_b32 v[102:103], v4 offset0:16 offset1:20
	ds_read2_b32 v[100:101], v4 offset0:24 offset1:28
	ds_read_b64 v[4:5], v166
	ds_read_b64 v[6:7], v166 offset:8
	s_or_b32 s8, s55, s50
	s_lshl_b32 s9, s54, 9
	v_add_u32_e32 v72, 0x2200, v166
	ds_read_b64 v[8:9], v72
	ds_read_b64 v[10:11], v72 offset:8
	s_or_b32 s8, s8, s9
	s_add_i32 s10, s8, 0x400
	s_ashr_i32 s11, s10, 31
	s_lshl_b64 s[10:11], s[10:11], 2
	s_waitcnt lgkmcnt(2)
	v_mfma_f32_32x32x16_bf16 v[18:33], v[0:3], v[4:7], 0
	s_add_u32 s10, s18, s10
	s_addc_u32 s11, s19, s11
	global_load_dword v104, v93, s[10:11]
	v_add_u32_e32 v78, 0x2220, v166
	v_add_u32_e32 v79, 0x2240, v166
	v_add_u32_e32 v86, 0x2260, v166
	s_waitcnt lgkmcnt(0)
	v_mfma_f32_32x32x16_bf16 v[34:49], v[0:3], v[8:11], 0
	ds_read_b64_tr_b16 v[0:1], v165 offset:3072
	ds_read_b64_tr_b16 v[2:3], v165 offset:3840
	ds_read_b64 v[4:5], v166 offset:32
	ds_read_b64 v[6:7], v166 offset:40
	ds_read_b64 v[8:9], v78
	ds_read_b64 v[10:11], v78 offset:8
	v_add_u32_e32 v178, 0x4000, v167
	v_add_u32_e32 v179, 0x2000, v167
	s_ashr_i32 s9, s8, 31
	s_lshl_b64 s[8:9], s[8:9], 14
	s_waitcnt lgkmcnt(2)
	v_mfma_f32_32x32x16_bf16 v[18:33], v[0:3], v[4:7], v[18:33]
	s_add_i32 s49, s49, s46
	s_cmpk_lt_i32 s49, 0x100
	s_waitcnt lgkmcnt(0)
	v_mfma_f32_32x32x16_bf16 v[34:49], v[0:3], v[8:11], v[34:49]
	ds_read_b64_tr_b16 v[0:1], v165 offset:6144
	ds_read_b64_tr_b16 v[2:3], v165 offset:6912
	ds_read_b64 v[4:5], v166 offset:64
	ds_read_b64 v[6:7], v166 offset:72
	ds_read_b64 v[8:9], v79
	ds_read_b64 v[10:11], v79 offset:8
	s_waitcnt lgkmcnt(2)
	v_mfma_f32_32x32x16_bf16 v[18:33], v[0:3], v[4:7], v[18:33]
	v_add_f32_e32 v4, 0, v12
	v_add_f32_e32 v12, v4, v13
	ds_read_b64_tr_b16 v[4:5], v165 offset:9216
	ds_read_b64_tr_b16 v[6:7], v165 offset:9984
	s_waitcnt lgkmcnt(2)
	v_mfma_f32_32x32x16_bf16 v[34:49], v[0:3], v[8:11], v[34:49]
	v_add_f32_e32 v0, v12, v14
	v_add_f32_e32 v8, v0, v15
	ds_read_b64 v[0:1], v166 offset:96
	ds_read_b64 v[2:3], v166 offset:104
	v_add_f32_e32 v102, v8, v102
	ds_read_b64 v[8:9], v86
	ds_read_b64 v[10:11], v86 offset:8
	s_waitcnt lgkmcnt(0)
	v_mfma_f32_32x32x16_bf16 v[34:49], v[4:7], v[8:11], v[34:49]
	v_mfma_f32_32x32x16_bf16 v[18:33], v[4:7], v[0:3], v[18:33]
	ds_read_b32 v2, v126
	ds_read_b32 v3, v127
	ds_read_b32 v12, v128
	ds_read_b32 v13, v129
	ds_read_b32 v14, v130
	ds_read_b32 v15, v131
	ds_read_b32 v16, v132
	ds_read_b32 v17, v133
	s_waitcnt lgkmcnt(6)
	v_cvt_f32_f16_e32 v1, v3
	v_cvt_f32_f16_e32 v0, v2
	v_cvt_f32_f16_sdwa v3, v3 dst_sel:DWORD dst_unused:UNUSED_PAD src0_sel:WORD_1
	v_cvt_f32_f16_sdwa v2, v2 dst_sel:DWORD dst_unused:UNUSED_PAD src0_sel:WORD_1
	s_waitcnt lgkmcnt(4)
	v_cvt_f32_f16_sdwa v7, v13 dst_sel:DWORD dst_unused:UNUSED_PAD src0_sel:WORD_1
	v_cvt_f32_f16_sdwa v6, v12 dst_sel:DWORD dst_unused:UNUSED_PAD src0_sel:WORD_1
	v_pk_mul_f32 v[4:5], v[34:35], v[2:3]
	s_nop 0
	v_pk_fma_f32 v[50:51], v[18:19], v[0:1], v[4:5] neg_lo:[0,0,1] neg_hi:[0,0,1]
	v_cvt_f32_f16_e32 v5, v13
	v_cvt_f32_f16_e32 v4, v12
	v_pk_mul_f32 v[2:3], v[18:19], v[2:3]
	s_nop 0
	v_pk_fma_f32 v[52:53], v[34:35], v[0:1], v[2:3]
	v_pk_mul_f32 v[0:1], v[36:37], v[6:7]
	s_waitcnt lgkmcnt(2)
	v_cvt_f32_f16_sdwa v3, v15 dst_sel:DWORD dst_unused:UNUSED_PAD src0_sel:WORD_1
	v_cvt_f32_f16_sdwa v2, v14 dst_sel:DWORD dst_unused:UNUSED_PAD src0_sel:WORD_1
	v_pk_fma_f32 v[54:55], v[20:21], v[4:5], v[0:1] neg_lo:[0,0,1] neg_hi:[0,0,1]
	v_cvt_f32_f16_e32 v1, v15
	v_cvt_f32_f16_e32 v0, v14
	v_pk_mul_f32 v[6:7], v[20:21], v[6:7]
	s_nop 0
	v_pk_fma_f32 v[56:57], v[36:37], v[4:5], v[6:7]
	v_pk_mul_f32 v[4:5], v[38:39], v[2:3]
	s_waitcnt lgkmcnt(0)
	v_cvt_f32_f16_sdwa v7, v17 dst_sel:DWORD dst_unused:UNUSED_PAD src0_sel:WORD_1
	v_cvt_f32_f16_sdwa v6, v16 dst_sel:DWORD dst_unused:UNUSED_PAD src0_sel:WORD_1
	v_pk_fma_f32 v[58:59], v[22:23], v[0:1], v[4:5] neg_lo:[0,0,1] neg_hi:[0,0,1]
	v_cvt_f32_f16_e32 v5, v17
	v_cvt_f32_f16_e32 v4, v16
	v_pk_mul_f32 v[2:3], v[22:23], v[2:3]
	s_nop 0
	v_pk_fma_f32 v[60:61], v[38:39], v[0:1], v[2:3]
	v_pk_mul_f32 v[0:1], v[40:41], v[6:7]
	v_pk_mul_f32 v[6:7], v[24:25], v[6:7]
	v_pk_fma_f32 v[62:63], v[24:25], v[4:5], v[0:1] neg_lo:[0,0,1] neg_hi:[0,0,1]
	ds_read_b32 v0, v134
	ds_read_b32 v2, v135
	ds_read_b32 v8, v136
	ds_read_b32 v9, v137
	ds_read_b32 v10, v138
	ds_read_b32 v11, v139
	ds_read_b32 v74, v140
	ds_read_b32 v75, v141
	s_waitcnt lgkmcnt(6)
	v_cvt_f32_f16_e32 v1, v2
	v_cvt_f32_f16_sdwa v3, v2 dst_sel:DWORD dst_unused:UNUSED_PAD src0_sel:WORD_1
	v_cvt_f32_f16_sdwa v2, v0 dst_sel:DWORD dst_unused:UNUSED_PAD src0_sel:WORD_1
	v_cvt_f32_f16_e32 v0, v0
	v_pk_fma_f32 v[64:65], v[40:41], v[4:5], v[6:7]
	s_waitcnt lgkmcnt(4)
	v_cvt_f32_f16_sdwa v7, v9 dst_sel:DWORD dst_unused:UNUSED_PAD src0_sel:WORD_1
	v_pk_mul_f32 v[4:5], v[42:43], v[2:3]
	v_cvt_f32_f16_sdwa v6, v8 dst_sel:DWORD dst_unused:UNUSED_PAD src0_sel:WORD_1
	v_pk_fma_f32 v[66:67], v[26:27], v[0:1], v[4:5] neg_lo:[0,0,1] neg_hi:[0,0,1]
	v_cvt_f32_f16_e32 v5, v9
	v_cvt_f32_f16_e32 v4, v8
	v_pk_mul_f32 v[2:3], v[26:27], v[2:3]
	ds_read_b64_tr_b16 v[16:17], v165 offset:64
	ds_read_b64_tr_b16 v[18:19], v165 offset:832
	v_pk_fma_f32 v[68:69], v[42:43], v[0:1], v[2:3]
	v_pk_mul_f32 v[0:1], v[44:45], v[6:7]
	s_waitcnt lgkmcnt(4)
	v_cvt_f32_f16_sdwa v27, v11 dst_sel:DWORD dst_unused:UNUSED_PAD src0_sel:WORD_1
	v_pk_fma_f32 v[70:71], v[28:29], v[4:5], v[0:1] neg_lo:[0,0,1] neg_hi:[0,0,1]
	v_pk_mul_f32 v[0:1], v[28:29], v[6:7]
	v_cvt_f32_f16_sdwa v26, v10 dst_sel:DWORD dst_unused:UNUSED_PAD src0_sel:WORD_1
	v_pk_fma_f32 v[80:81], v[44:45], v[4:5], v[0:1]
	ds_read_b64 v[0:1], v166
	ds_read_b64 v[2:3], v166 offset:8
	ds_read_b64 v[20:21], v72
	ds_read_b64 v[22:23], v72 offset:8
	v_cvt_f32_f16_e32 v25, v11
	v_cvt_f32_f16_e32 v24, v10
	v_pk_mul_f32 v[28:29], v[46:47], v[26:27]
	v_pk_mul_f32 v[26:27], v[30:31], v[26:27]
	s_waitcnt lgkmcnt(2)
	v_mfma_f32_32x32x16_bf16 v[0:15], v[16:19], v[0:3], 0
	v_fma_f32 v82, v30, v24, -v28
	v_fma_f32 v83, v31, v25, -v29
	v_fma_f32 v46, v46, v24, v26
	v_fma_f32 v47, v47, v25, v27
	ds_read_b64_tr_b16 v[34:35], v165 offset:3136
	ds_read_b64_tr_b16 v[36:37], v165 offset:3904
	ds_read_b64 v[38:39], v166 offset:32
	ds_read_b64 v[40:41], v166 offset:40
	ds_read_b64 v[42:43], v78
	ds_read_b64 v[44:45], v78 offset:8
	v_cvt_f32_f16_sdwa v73, v75 dst_sel:DWORD dst_unused:UNUSED_PAD src0_sel:WORD_1
	s_waitcnt lgkmcnt(6)
	v_mfma_f32_32x32x16_bf16 v[16:31], v[16:19], v[20:23], 0
	v_cvt_f32_f16_sdwa v72, v74 dst_sel:DWORD dst_unused:UNUSED_PAD src0_sel:WORD_1
	v_cvt_f32_f16_e32 v75, v75
	v_cvt_f32_f16_e32 v74, v74
	v_mul_f32_e64 v76, v48, v72
	v_mul_f32_e64 v77, v49, v73
	v_cvt_pk_bf16_f32 v68, v68, v69
	v_pk_fma_f32 v[84:85], v[32:33], v[74:75], v[76:77] neg_lo:[0,0,1] neg_hi:[0,0,1]
	s_waitcnt lgkmcnt(0)
	v_mfma_f32_32x32x16_bf16 v[16:31], v[34:37], v[42:45], v[16:31]
	v_mul_f32_e64 v32, v32, v72
	v_mul_f32_e64 v33, v33, v73
	v_cvt_pk_bf16_f32 v73, v54, v55
	v_fma_f32 v48, v48, v74, v32
	v_fma_f32 v49, v49, v75, v33
	v_cvt_pk_bf16_f32 v74, v58, v59
	v_cvt_pk_bf16_f32 v69, v80, v81
	v_cvt_pk_bf16_f32 v76, v52, v53
	v_cvt_pk_bf16_f32 v72, v50, v51
	v_mfma_f32_32x32x16_bf16 v[0:15], v[34:37], v[38:41], v[0:15]
	ds_read_b64_tr_b16 v[38:39], v165 offset:6208
	ds_read_b64_tr_b16 v[40:41], v165 offset:6976
	ds_read_b64 v[32:33], v166 offset:64
	ds_read_b64 v[34:35], v166 offset:72
	ds_read_b64 v[42:43], v79
	ds_read_b64 v[44:45], v79 offset:8
	v_cvt_pk_bf16_f32 v79, v64, v65
	v_cvt_pk_bf16_f32 v64, v66, v67
	v_cvt_pk_bf16_f32 v66, v82, v83
	s_waitcnt lgkmcnt(0)
	v_mfma_f32_32x32x16_bf16 v[16:31], v[38:41], v[42:45], v[16:31]
	v_cvt_pk_bf16_f32 v67, v84, v85
	v_cvt_pk_bf16_f32 v75, v62, v63
	v_cvt_pk_bf16_f32 v77, v56, v57
	v_cvt_pk_bf16_f32 v65, v70, v71
	v_cvt_pk_bf16_f32 v71, v48, v49
	v_cvt_pk_bf16_f32 v70, v46, v47
	v_cvt_pk_bf16_f32 v78, v60, v61
	v_mfma_f32_32x32x16_bf16 v[0:15], v[38:41], v[32:35], v[0:15]
	ds_read_b64_tr_b16 v[32:33], v165 offset:9280
	ds_read_b64_tr_b16 v[34:35], v165 offset:10048
	ds_read_b64 v[36:37], v166 offset:96
	ds_read_b64 v[38:39], v166 offset:104
	ds_read_b64 v[40:41], v86
	ds_read_b64 v[42:43], v86 offset:8
	s_waitcnt lgkmcnt(0)
	v_mfma_f32_32x32x16_bf16 v[16:31], v[32:35], v[40:43], v[16:31]
	v_mfma_f32_32x32x16_bf16 v[0:15], v[32:35], v[36:39], v[0:15]
	ds_read_b32 v36, v142
	ds_read_b32 v37, v143
	ds_read_b32 v54, v144
	ds_read_b32 v55, v145
	ds_read_b32 v58, v146
	ds_read_b32 v59, v147
	ds_read_b32 v105, v148
	ds_read_b32 v176, v149
	ds_read_b64 v[80:81], v167
	ds_read_b64 v[82:83], v167 offset:16
	s_waitcnt lgkmcnt(8)
	v_cvt_f32_f16_e32 v53, v37
	v_cvt_f32_f16_e32 v52, v36
	v_cvt_f32_f16_sdwa v37, v37 dst_sel:DWORD dst_unused:UNUSED_PAD src0_sel:WORD_1
	v_cvt_f32_f16_sdwa v36, v36 dst_sel:DWORD dst_unused:UNUSED_PAD src0_sel:WORD_1
	s_waitcnt lgkmcnt(6)
	v_cvt_f32_f16_sdwa v57, v55 dst_sel:DWORD dst_unused:UNUSED_PAD src0_sel:WORD_1
	ds_read_b64 v[48:49], v178 offset:1024
	ds_read_b64 v[50:51], v178 offset:1040
	v_cvt_f32_f16_sdwa v56, v54 dst_sel:DWORD dst_unused:UNUSED_PAD src0_sel:WORD_1
	v_pk_mul_f32 v[32:33], v[16:17], v[36:37]
	s_waitcnt lgkmcnt(6)
	v_cvt_f32_f16_e32 v169, v59
	v_pk_fma_f32 v[84:85], v[0:1], v[52:53], v[32:33] neg_lo:[0,0,1] neg_hi:[0,0,1]
	v_pk_mul_f32 v[0:1], v[0:1], v[36:37]
	s_waitcnt lgkmcnt(2)
	v_mfma_f32_32x32x16_bf16 v[32:47], v[80:83], v[72:75], 0
	v_fma_f32 v86, v16, v52, v0
	v_fma_f32 v87, v17, v53, v1
	v_cvt_f32_f16_e32 v1, v55
	v_cvt_f32_f16_e32 v0, v54
	ds_read_b64 v[52:53], v179 offset:512
	ds_read_b64 v[54:55], v179 offset:528
	v_pk_mul_f32 v[16:17], v[18:19], v[56:57]
	ds_read_b32 v180, v150
	ds_read_b32 v181, v151
	ds_read_b32 v182, v152
	ds_read_b32 v183, v153
	ds_read_b32 v184, v154
	ds_read_b32 v185, v155
	ds_read_b32 v186, v156
	ds_read_b32 v187, v157
	v_pk_fma_f32 v[88:89], v[2:3], v[0:1], v[16:17] neg_lo:[0,0,1] neg_hi:[0,0,1]
	v_pk_mul_f32 v[2:3], v[2:3], v[56:57]
	s_waitcnt lgkmcnt(10)
	v_mfma_f32_32x32x16_bf16 v[32:47], v[48:51], v[76:79], v[32:47]
	v_fma_f32 v90, v18, v0, v2
	v_fma_f32 v91, v19, v1, v3
	ds_read_b64 v[0:1], v167 offset:32
	ds_read_b64 v[2:3], v167 offset:48
	v_cvt_f32_f16_e32 v168, v58
	v_cvt_f32_f16_sdwa v171, v59 dst_sel:DWORD dst_unused:UNUSED_PAD src0_sel:WORD_1
	v_cvt_f32_f16_sdwa v170, v58 dst_sel:DWORD dst_unused:UNUSED_PAD src0_sel:WORD_1
	v_cvt_f32_f16_e32 v175, v176
	v_cvt_f32_f16_sdwa v177, v176 dst_sel:DWORD dst_unused:UNUSED_PAD src0_sel:WORD_1
	s_waitcnt lgkmcnt(10)
	v_mfma_f32_32x32x16_bf16 v[48:63], v[52:55], v[72:75], 0
	v_mul_f32_e64 v16, v20, v170
	v_mul_f32_e64 v17, v21, v171
	v_cvt_f32_f16_sdwa v176, v105 dst_sel:DWORD dst_unused:UNUSED_PAD src0_sel:WORD_1
	v_fma_f32 v172, v4, v168, -v16
	v_fma_f32 v173, v5, v169, -v17
	ds_read_b64 v[16:17], v178 offset:1056
	ds_read_b64 v[18:19], v178 offset:1072
	v_cvt_f32_f16_e32 v174, v105
	v_pk_mul_f32 v[4:5], v[4:5], v[170:171]
	s_waitcnt lgkmcnt(10)
	v_cvt_f32_f16_sdwa v171, v181 dst_sel:DWORD dst_unused:UNUSED_PAD src0_sel:WORD_1
	v_mfma_f32_32x32x16_bf16 v[48:63], v[80:83], v[76:79], v[48:63]
	ds_read_b64 v[80:81], v179 offset:544
	ds_read_b64 v[82:83], v179 offset:560
	v_fma_f32 v20, v20, v168, v4
	v_fma_f32 v21, v21, v169, v5
	v_mul_f32_e64 v4, v22, v176
	v_mul_f32_e64 v5, v23, v177
	v_cvt_f32_f16_sdwa v170, v180 dst_sel:DWORD dst_unused:UNUSED_PAD src0_sel:WORD_1
	v_pk_fma_f32 v[168:169], v[6:7], v[174:175], v[4:5] neg_lo:[0,0,1] neg_hi:[0,0,1]
	v_cvt_f32_f16_e32 v5, v181
	v_cvt_f32_f16_e32 v4, v180
	s_waitcnt lgkmcnt(4)
	v_mfma_f32_32x32x16_bf16 v[32:47], v[0:3], v[64:67], v[32:47]
	v_mul_f32_e64 v6, v6, v176
	v_mul_f32_e64 v7, v7, v177
	s_waitcnt lgkmcnt(2)
	v_mfma_f32_32x32x16_bf16 v[32:47], v[16:19], v[68:71], v[32:47]
	v_fma_f32 v16, v22, v174, v6
	v_fma_f32 v17, v23, v175, v7
	v_mul_f32_e64 v6, v24, v170
	v_mul_f32_e64 v7, v25, v171
	v_fma_f32 v22, v8, v4, -v6
	v_fma_f32 v23, v9, v5, -v7
	v_pk_mul_f32 v[6:7], v[8:9], v[170:171]
	v_cvt_f32_f16_sdwa v171, v183 dst_sel:DWORD dst_unused:UNUSED_PAD src0_sel:WORD_1
	v_pk_fma_f32 v[8:9], v[24:25], v[4:5], v[6:7]
	s_waitcnt lgkmcnt(0)
	v_mfma_f32_32x32x16_bf16 v[48:63], v[80:83], v[64:67], v[48:63]
	ds_read_b64 v[4:5], v167 offset:64
	ds_read_b64 v[6:7], v167 offset:80
	v_cvt_f32_f16_sdwa v170, v182 dst_sel:DWORD dst_unused:UNUSED_PAD src0_sel:WORD_1
	v_cvt_f32_f16_e32 v25, v183
	v_cvt_f32_f16_e32 v24, v182
	v_cvt_pk_bf16_f32 v80, v84, v85
	v_cvt_pk_bf16_f32 v81, v88, v89
	v_cvt_pk_bf16_f32 v82, v172, v173
	v_mfma_f32_32x32x16_bf16 v[48:63], v[0:3], v[68:71], v[48:63]
	v_mul_f32_e64 v0, v26, v170
	v_mul_f32_e64 v1, v27, v171
	v_cvt_pk_bf16_f32 v83, v168, v169
	v_fma_f32 v174, v10, v24, -v0
	v_fma_f32 v175, v11, v25, -v1
	ds_read_b64 v[0:1], v178 offset:1088
	ds_read_b64 v[2:3], v178 offset:1104
	v_cvt_pk_bf16_f32 v89, v90, v91
	v_cvt_pk_bf16_f32 v91, v16, v17
	ds_read_b64 v[16:17], v179 offset:576
	ds_read_b64 v[18:19], v179 offset:592
	s_waitcnt lgkmcnt(4)
	v_mfma_f32_32x32x16_bf16 v[32:47], v[4:7], v[80:83], v[32:47]
	v_cvt_f32_f16_sdwa v169, v185 dst_sel:DWORD dst_unused:UNUSED_PAD src0_sel:WORD_1
	v_cvt_f32_f16_sdwa v168, v184 dst_sel:DWORD dst_unused:UNUSED_PAD src0_sel:WORD_1
	v_cvt_f32_f16_e32 v85, v185
	v_cvt_f32_f16_e32 v84, v184
	v_cvt_pk_bf16_f32 v88, v86, v87
	v_cvt_pk_bf16_f32 v90, v20, v21
	s_waitcnt lgkmcnt(0)
	v_mfma_f32_32x32x16_bf16 v[48:63], v[16:19], v[80:83], v[48:63]
	v_cvt_f32_f16_sdwa v19, v187 dst_sel:DWORD dst_unused:UNUSED_PAD src0_sel:WORD_1
	v_cvt_f32_f16_sdwa v18, v186 dst_sel:DWORD dst_unused:UNUSED_PAD src0_sel:WORD_1
	v_cvt_f32_f16_e32 v17, v187
	v_cvt_f32_f16_e32 v16, v186
	v_mfma_f32_32x32x16_bf16 v[32:47], v[0:3], v[88:91], v[32:47]
	v_mul_f32_e64 v0, v10, v170
	v_mul_f32_e64 v1, v11, v171
	v_fma_f32 v10, v26, v24, v0
	v_fma_f32 v11, v27, v25, v1
	v_mul_f32_e64 v0, v28, v168
	v_mul_f32_e64 v1, v29, v169
	v_pk_fma_f32 v[20:21], v[12:13], v[84:85], v[0:1] neg_lo:[0,0,1] neg_hi:[0,0,1]
	v_pk_mul_f32 v[0:1], v[12:13], v[168:169]
	v_cvt_pk_bf16_f32 v168, v8, v9
	v_pk_fma_f32 v[12:13], v[28:29], v[84:85], v[0:1]
	ds_read_b64 v[0:1], v167 offset:96
	ds_read_b64 v[2:3], v167 offset:112
	v_cvt_pk_bf16_f32 v169, v10, v11
	ds_read_b64 v[8:9], v179 offset:608
	ds_read_b64 v[10:11], v179 offset:624
	v_mfma_f32_32x32x16_bf16 v[48:63], v[4:7], v[88:91], v[48:63]
	v_mul_f32_e64 v4, v30, v18
	v_mul_f32_e64 v5, v31, v19
	v_cvt_pk_bf16_f32 v84, v22, v23
	v_fma_f32 v4, v14, v16, -v4
	v_fma_f32 v5, v15, v17, -v5
	v_cvt_pk_bf16_f32 v85, v174, v175
	v_cvt_pk_bf16_f32 v86, v20, v21
	v_cvt_pk_bf16_f32 v87, v4, v5
	ds_read_b64 v[4:5], v178 offset:1120
	ds_read_b64 v[6:7], v178 offset:1136
	v_pk_mul_f32 v[14:15], v[14:15], v[18:19]
	s_waitcnt lgkmcnt(4)
	v_mfma_f32_32x32x16_bf16 v[32:47], v[0:3], v[84:87], v[32:47]
	v_fma_f32 v14, v30, v16, v14
	v_fma_f32 v15, v31, v17, v15
	v_cvt_pk_bf16_f32 v170, v12, v13
	v_cvt_pk_bf16_f32 v171, v14, v15
	s_waitcnt lgkmcnt(2)
	v_mfma_f32_32x32x16_bf16 v[48:63], v[8:11], v[84:87], v[48:63]
	s_waitcnt lgkmcnt(0)
	v_mfma_f32_32x32x16_bf16 v[32:47], v[4:7], v[168:171], v[32:47]
	v_add_f32_e32 v4, v102, v103
	v_add_f32_e32 v4, v4, v100
	v_add_f32_e32 v4, v4, v101
	v_add_f32_e32 v4, 0x358637bd, v4
	v_mul_f32_e32 v5, 0x4b800000, v4
	v_cmp_gt_f32_e32 vcc, s44, v4
	v_lshl_add_u64 v[102:103], v[98:99], 0, s[8:9]
	v_mfma_f32_32x32x16_bf16 v[48:63], v[0:3], v[168:171], v[48:63]
	v_cndmask_b32_e32 v4, v4, v5, vcc
	v_rsq_f32_e32 v4, v4
	s_nop 0
	v_mul_f32_e32 v5, 0x45800000, v4
	v_cndmask_b32_e32 v105, v4, v5, vcc
	s_waitcnt vmcnt(0)
	v_pk_mul_f32 v[100:101], v[104:105], s[26:27] op_sel_hi:[1,0]
	s_nop 0
	v_fma_f32 v0, v101, v32, v100
	s_nop 2
	v_mul_f32_e32 v1, v101, v48
	v_cvt_pk_bf16_f32 v0, v0, v1
	global_store_dword v[102:103], v0, off
	v_fma_f32 v0, v101, v33, v100
	v_mul_f32_e32 v1, v101, v49
	v_cvt_pk_bf16_f32 v0, v0, v1
	global_store_dword v[102:103], v0, off offset:256
	v_fma_f32 v0, v101, v34, v100
	v_mul_f32_e32 v1, v101, v50
	v_cvt_pk_bf16_f32 v0, v0, v1
	global_store_dword v[102:103], v0, off offset:512
	v_fma_f32 v0, v101, v35, v100
	v_mul_f32_e32 v1, v101, v51
	v_cvt_pk_bf16_f32 v0, v0, v1
	global_store_dword v[102:103], v0, off offset:768
	v_fma_f32 v0, v101, v36, v100
	v_mul_f32_e32 v1, v101, v52
	v_cvt_pk_bf16_f32 v0, v0, v1
	global_store_dword v[102:103], v0, off offset:2048
	v_fma_f32 v0, v101, v37, v100
	v_mul_f32_e32 v1, v101, v53
	v_cvt_pk_bf16_f32 v0, v0, v1
	global_store_dword v[102:103], v0, off offset:2304
	v_fma_f32 v0, v101, v38, v100
	v_mul_f32_e32 v1, v101, v54
	v_cvt_pk_bf16_f32 v0, v0, v1
	global_store_dword v[102:103], v0, off offset:2560
	v_fma_f32 v0, v101, v39, v100
	v_mul_f32_e32 v1, v101, v55
	v_cvt_pk_bf16_f32 v0, v0, v1
	global_store_dword v[102:103], v0, off offset:2816
	v_fma_f32 v0, v101, v40, v100
	v_add_u32_e32 v40, 0x1000, v167
	ds_read_b64 v[32:33], v40 offset:256
	ds_read_b64 v[34:35], v40 offset:272
	v_add_co_u32_e32 v36, vcc, s1, v102
	v_mul_f32_e32 v1, v101, v56
	s_nop 0
	v_addc_co_u32_e32 v37, vcc, 0, v103, vcc
	v_add_co_u32_e32 v48, vcc, s45, v102
	v_cvt_pk_bf16_f32 v0, v0, v1
	s_nop 0
	v_addc_co_u32_e32 v49, vcc, 0, v103, vcc
	global_store_dword v[48:49], v0, off offset:-4096
	v_fma_f32 v0, v101, v41, v100
	v_mul_f32_e32 v1, v101, v57
	v_cvt_pk_bf16_f32 v0, v0, v1
	global_store_dword v[36:37], v0, off offset:256
	v_fma_f32 v0, v101, v42, v100
	v_mul_f32_e32 v1, v101, v58
	v_add_u32_e32 v41, 0x5000, v167
	v_cvt_pk_bf16_f32 v0, v0, v1
	ds_read_b64 v[16:17], v41 offset:1280
	ds_read_b64 v[18:19], v41 offset:1296
	global_store_dword v[36:37], v0, off offset:512
	v_fma_f32 v20, v101, v43, v100
	s_waitcnt lgkmcnt(2)
	v_mfma_f32_32x32x16_bf16 v[0:15], v[32:35], v[72:75], 0
	v_mul_f32_e32 v21, v101, v59
	v_cvt_pk_bf16_f32 v20, v20, v21
	v_add_u32_e32 v42, 0x3000, v167
	global_store_dword v[36:37], v20, off offset:768
	ds_read_b64 v[20:21], v42 offset:768
	ds_read_b64 v[22:23], v42 offset:784
	v_fma_f32 v24, v101, v44, v100
	v_mul_f32_e32 v25, v101, v60
	s_waitcnt lgkmcnt(2)
	v_mfma_f32_32x32x16_bf16 v[0:15], v[16:19], v[76:79], v[0:15]
	v_cvt_pk_bf16_f32 v16, v24, v25
	global_store_dword v[36:37], v16, off offset:2048
	v_fma_f32 v16, v101, v45, v100
	v_mul_f32_e32 v17, v101, v61
	v_cvt_pk_bf16_f32 v16, v16, v17
	global_store_dword v[36:37], v16, off offset:2304
	v_fma_f32 v38, v101, v46, v100
	s_waitcnt lgkmcnt(0)
	v_mfma_f32_32x32x16_bf16 v[16:31], v[20:23], v[72:75], 0
	v_mul_f32_e32 v39, v101, v62
	v_cvt_pk_bf16_f32 v38, v38, v39
	global_store_dword v[36:37], v38, off offset:2560
	v_fma_f32 v38, v101, v47, v100
	v_mul_f32_e32 v39, v101, v63
	v_cvt_pk_bf16_f32 v38, v38, v39
	global_store_dword v[36:37], v38, off offset:2816
	v_mfma_f32_32x32x16_bf16 v[16:31], v[32:35], v[76:79], v[16:31]
	ds_read_b64 v[32:33], v40 offset:288
	ds_read_b64 v[34:35], v40 offset:304
	ds_read_b64 v[36:37], v41 offset:1312
	ds_read_b64 v[38:39], v41 offset:1328
	s_waitcnt lgkmcnt(2)
	v_mfma_f32_32x32x16_bf16 v[0:15], v[32:35], v[64:67], v[0:15]
	s_waitcnt lgkmcnt(0)
	v_mfma_f32_32x32x16_bf16 v[0:15], v[36:39], v[68:71], v[0:15]
	ds_read_b64 v[36:37], v42 offset:800
	ds_read_b64 v[38:39], v42 offset:816
	s_waitcnt lgkmcnt(0)
	v_mfma_f32_32x32x16_bf16 v[16:31], v[36:39], v[64:67], v[16:31]
	ds_read_b64 v[36:37], v41 offset:1344
	ds_read_b64 v[38:39], v41 offset:1360
	v_mfma_f32_32x32x16_bf16 v[16:31], v[32:35], v[68:71], v[16:31]
	ds_read_b64 v[32:33], v40 offset:320
	ds_read_b64 v[34:35], v40 offset:336
	s_waitcnt lgkmcnt(0)
	v_mfma_f32_32x32x16_bf16 v[0:15], v[32:35], v[80:83], v[0:15]
	v_mfma_f32_32x32x16_bf16 v[0:15], v[36:39], v[88:91], v[0:15]
	ds_read_b64 v[36:37], v42 offset:832
	ds_read_b64 v[38:39], v42 offset:848
	s_waitcnt lgkmcnt(0)
	v_mfma_f32_32x32x16_bf16 v[16:31], v[36:39], v[80:83], v[16:31]
	ds_read_b64 v[36:37], v41 offset:1376
	ds_read_b64 v[38:39], v41 offset:1392
	v_mfma_f32_32x32x16_bf16 v[16:31], v[32:35], v[88:91], v[16:31]
	ds_read_b64 v[32:33], v40 offset:352
	ds_read_b64 v[34:35], v40 offset:368
	s_waitcnt lgkmcnt(0)
	v_mfma_f32_32x32x16_bf16 v[0:15], v[32:35], v[84:87], v[0:15]
	v_mfma_f32_32x32x16_bf16 v[0:15], v[36:39], v[168:171], v[0:15]
	ds_read_b64 v[36:37], v42 offset:864
	ds_read_b64 v[38:39], v42 offset:880
	s_waitcnt lgkmcnt(0)
	v_mfma_f32_32x32x16_bf16 v[16:31], v[36:39], v[84:87], v[16:31]
	s_nop 8
	v_fma_f32 v0, v101, v0, v100
	v_mfma_f32_32x32x16_bf16 v[16:31], v[32:35], v[168:171], v[16:31]
	s_nop 11
	v_mul_f32_e32 v16, v101, v16
	v_cvt_pk_bf16_f32 v0, v0, v16
	global_store_dword v[48:49], v0, off
	v_fma_f32 v0, v101, v1, v100
	v_mul_f32_e32 v1, v101, v17
	v_cvt_pk_bf16_f32 v0, v0, v1
	global_store_dword v[48:49], v0, off offset:256
	v_fma_f32 v0, v101, v2, v100
	v_mul_f32_e32 v1, v101, v18
	v_cvt_pk_bf16_f32 v0, v0, v1
	global_store_dword v[48:49], v0, off offset:512
	v_fma_f32 v0, v101, v3, v100
	v_mul_f32_e32 v1, v101, v19
	v_cvt_pk_bf16_f32 v0, v0, v1
	global_store_dword v[48:49], v0, off offset:768
	v_fma_f32 v0, v101, v4, v100
	v_mul_f32_e32 v1, v101, v20
	v_cvt_pk_bf16_f32 v0, v0, v1
	global_store_dword v[48:49], v0, off offset:2048
	v_fma_f32 v0, v101, v5, v100
	v_mul_f32_e32 v1, v101, v21
	v_cvt_pk_bf16_f32 v0, v0, v1
	global_store_dword v[48:49], v0, off offset:2304
	v_fma_f32 v0, v101, v6, v100
	v_mul_f32_e32 v1, v101, v22
	v_cvt_pk_bf16_f32 v0, v0, v1
	global_store_dword v[48:49], v0, off offset:2560
	v_fma_f32 v0, v101, v7, v100
	v_mul_f32_e32 v1, v101, v23
	v_cvt_pk_bf16_f32 v0, v0, v1
	global_store_dword v[48:49], v0, off offset:2816
	v_fma_f32 v0, v101, v8, v100
	v_mul_f32_e32 v1, v101, v24
	v_cvt_pk_bf16_f32 v2, v0, v1
	v_add_co_u32_e32 v0, vcc, s38, v102
	v_mul_f32_e32 v3, v101, v25
	s_nop 0
	v_addc_co_u32_e32 v1, vcc, 0, v103, vcc
	global_store_dword v[0:1], v2, off
	v_fma_f32 v2, v101, v9, v100
	v_cvt_pk_bf16_f32 v2, v2, v3
	global_store_dword v[0:1], v2, off offset:256
	v_fma_f32 v2, v101, v10, v100
	v_mul_f32_e32 v3, v101, v26
	v_cvt_pk_bf16_f32 v2, v2, v3
	global_store_dword v[0:1], v2, off offset:512
	v_fma_f32 v2, v101, v11, v100
	v_mul_f32_e32 v3, v101, v27
	v_cvt_pk_bf16_f32 v2, v2, v3
	global_store_dword v[0:1], v2, off offset:768
	v_fma_f32 v2, v101, v12, v100
	v_mul_f32_e32 v3, v101, v28
	v_cvt_pk_bf16_f32 v2, v2, v3
	global_store_dword v[0:1], v2, off offset:2048
	v_fma_f32 v2, v101, v13, v100
	v_mul_f32_e32 v3, v101, v29
	v_cvt_pk_bf16_f32 v2, v2, v3
	global_store_dword v[0:1], v2, off offset:2304
	v_fma_f32 v2, v101, v14, v100
	v_mul_f32_e32 v3, v101, v30
	v_cvt_pk_bf16_f32 v2, v2, v3
	global_store_dword v[0:1], v2, off offset:2560
	v_mul_f32_e32 v2, v101, v31
	v_fmac_f32_e32 v100, v101, v15
	v_cvt_pk_bf16_f32 v2, v100, v2
	global_store_dword v[0:1], v2, off offset:2816
	s_barrier
	s_cbranch_scc0 .LBB0_2484
